# removed on the static-priority version: the redundant lgkmcnt(0) wait after each pre-MFMA barrier (already waited before the barrier)
# speedup vs baseline: 1.0102x; 1.0001x over previous
.Lsprio_0:
.LBB0_214:
	s_add_u32 s28, s30, 0xfffc0080
	s_addc_u32 s36, s31, -1
	s_add_i32 s43, 0, 0x10000
	s_cmp_eq_u32 s26, 12
	s_cselect_b32 s53, s2, s36
	s_cselect_b32 s52, s3, s28
	v_add_u32_e32 v157, s43, v153
	s_cselect_b32 s37, s13, s25
	s_cselect_b32 s36, s16, s24
	s_add_i32 s28, 0, 0x14000
	ds_read_b128 v[130:133], v157
	ds_read_b128 v[148:151], v157 offset:1024
	ds_read_b128 v[158:161], v157 offset:2048
	ds_read_b128 v[162:165], v157 offset:3072
	v_add_u32_e32 v157, s28, v153
	ds_read_b128 v[166:169], v157
	ds_read_b128 v[170:173], v157 offset:1024
	ds_read_b128 v[174:177], v157 offset:2048
	ds_read_b128 v[178:181], v157 offset:3072
	v_lshl_add_u64 v[192:193], s[30:31], 0, v[144:145]
	s_add_i32 m0, s75, 0xc000
	ds_read_b128 v[184:187], v156
	ds_read_b128 v[188:191], v156 offset:1024
	ds_read_b128 v[196:199], v156 offset:2048
	ds_read_b128 v[210:213], v156 offset:3072
	ds_read_b128 v[214:217], v156 offset:4096
	ds_read_b128 v[218:221], v156 offset:5120
	ds_read_b128 v[222:225], v156 offset:6144
	ds_read_b128 v[226:229], v156 offset:7168
	global_load_lds_dwordx4 v[192:193], off
	v_lshl_add_u64 v[192:193], s[30:31], 0, v[146:147]
	s_add_i32 m0, s75, 0xe000
	s_nop 0
	global_load_lds_dwordx4 v[192:193], off
	s_waitcnt vmcnt(8)
	s_waitcnt lgkmcnt(0)
	s_barrier
	v_mfma_f32_16x16x32_bf16 v[126:129], v[130:133], v[184:187], v[126:129]
	v_mfma_f32_16x16x32_bf16 v[122:125], v[158:161], v[184:187], v[122:125]
	v_mfma_f32_16x16x32_bf16 v[110:113], v[130:133], v[196:199], v[110:113]
	v_mfma_f32_16x16x32_bf16 v[106:109], v[158:161], v[196:199], v[106:109]
	v_mfma_f32_16x16x32_bf16 v[94:97], v[130:133], v[214:217], v[94:97]
	v_mfma_f32_16x16x32_bf16 v[90:93], v[158:161], v[214:217], v[90:93]
	v_mfma_f32_16x16x32_bf16 v[78:81], v[130:133], v[222:225], v[78:81]
	v_mfma_f32_16x16x32_bf16 v[74:77], v[158:161], v[222:225], v[74:77]
	v_mfma_f32_16x16x32_bf16 v[126:129], v[148:151], v[188:191], v[126:129]
	v_mfma_f32_16x16x32_bf16 v[122:125], v[162:165], v[188:191], v[122:125]
	v_mfma_f32_16x16x32_bf16 v[110:113], v[148:151], v[210:213], v[110:113]
	v_mfma_f32_16x16x32_bf16 v[106:109], v[162:165], v[210:213], v[106:109]
	v_mfma_f32_16x16x32_bf16 v[94:97], v[148:151], v[218:221], v[94:97]
	v_mfma_f32_16x16x32_bf16 v[90:93], v[162:165], v[218:221], v[90:93]
	v_mfma_f32_16x16x32_bf16 v[78:81], v[148:151], v[226:229], v[78:81]
	v_mfma_f32_16x16x32_bf16 v[74:77], v[162:165], v[226:229], v[74:77]
	v_mfma_f32_16x16x32_bf16 v[118:121], v[166:169], v[184:187], v[118:121]
	v_mfma_f32_16x16x32_bf16 v[114:117], v[174:177], v[184:187], v[114:117]
	v_mfma_f32_16x16x32_bf16 v[102:105], v[166:169], v[196:199], v[102:105]
	v_mfma_f32_16x16x32_bf16 v[98:101], v[174:177], v[196:199], v[98:101]
	v_mfma_f32_16x16x32_bf16 v[86:89], v[166:169], v[214:217], v[86:89]
	v_mfma_f32_16x16x32_bf16 v[82:85], v[174:177], v[214:217], v[82:85]
	v_mfma_f32_16x16x32_bf16 v[70:73], v[166:169], v[222:225], v[70:73]
	v_mfma_f32_16x16x32_bf16 v[66:69], v[174:177], v[222:225], v[66:69]
	v_mfma_f32_16x16x32_bf16 v[118:121], v[170:173], v[188:191], v[118:121]
	v_mfma_f32_16x16x32_bf16 v[114:117], v[178:181], v[188:191], v[114:117]
	v_mfma_f32_16x16x32_bf16 v[102:105], v[170:173], v[210:213], v[102:105]
	v_mfma_f32_16x16x32_bf16 v[98:101], v[178:181], v[210:213], v[98:101]
	v_mfma_f32_16x16x32_bf16 v[86:89], v[170:173], v[218:221], v[86:89]
	v_mfma_f32_16x16x32_bf16 v[82:85], v[178:181], v[218:221], v[82:85]
	v_mfma_f32_16x16x32_bf16 v[70:73], v[170:173], v[226:229], v[70:73]
	v_mfma_f32_16x16x32_bf16 v[66:69], v[178:181], v[226:229], v[66:69]
	s_barrier
	s_add_i32 s43, s43, s17
	v_lshl_add_u64 v[192:193], s[36:37], 0, v[0:1]
	s_mov_b32 m0, s43
	ds_read_b128 v[184:187], v156 offset:16384
	ds_read_b128 v[188:191], v156 offset:17408
	ds_read_b128 v[196:199], v156 offset:18432
	ds_read_b128 v[210:213], v156 offset:19456
	ds_read_b128 v[214:217], v156 offset:20480
	ds_read_b128 v[218:221], v156 offset:21504
	ds_read_b128 v[222:225], v156 offset:22528
	ds_read_b128 v[226:229], v156 offset:23552
	global_load_lds_dwordx4 v[192:193], off
	s_add_i32 m0, s43, 0x2000
	s_add_u32 s70, s36, 0x40000
	v_lshl_add_u64 v[202:203], s[36:37], 0, v[134:135]
	s_addc_u32 s71, s37, 0
	s_add_i32 s28, s28, s17
	global_load_lds_dwordx4 v[202:203], off
	v_lshl_add_u64 v[230:231], s[70:71], 0, v[0:1]
	s_mov_b32 m0, s28
	v_lshl_add_u64 v[232:233], s[52:53], 0, v[136:137]
	global_load_lds_dwordx4 v[230:231], off
	v_lshl_add_u64 v[230:231], s[70:71], 0, v[134:135]
	s_add_i32 m0, s28, 0x2000
	s_nop 0
	global_load_lds_dwordx4 v[230:231], off
	v_lshl_add_u64 v[230:231], s[52:53], 0, v[138:139]
	s_mov_b32 m0, s75
	s_nop 0
	global_load_lds_dwordx4 v[230:231], off
	s_mov_b32 m0, s58
	s_nop 0
	global_load_lds_dwordx4 v[232:233], off
	s_waitcnt vmcnt(8)
	s_waitcnt lgkmcnt(0)
	s_barrier
	v_mfma_f32_16x16x32_bf16 v[62:65], v[130:133], v[184:187], v[62:65]
	v_mfma_f32_16x16x32_bf16 v[58:61], v[158:161], v[184:187], v[58:61]
	v_mfma_f32_16x16x32_bf16 v[46:49], v[130:133], v[196:199], v[46:49]
	v_mfma_f32_16x16x32_bf16 v[42:45], v[158:161], v[196:199], v[42:45]
	v_mfma_f32_16x16x32_bf16 v[30:33], v[130:133], v[214:217], v[30:33]
	v_mfma_f32_16x16x32_bf16 v[26:29], v[158:161], v[214:217], v[26:29]
	v_mfma_f32_16x16x32_bf16 v[14:17], v[130:133], v[222:225], v[14:17]
	v_mfma_f32_16x16x32_bf16 v[10:13], v[158:161], v[222:225], v[10:13]
	v_mfma_f32_16x16x32_bf16 v[62:65], v[148:151], v[188:191], v[62:65]
	v_mfma_f32_16x16x32_bf16 v[58:61], v[162:165], v[188:191], v[58:61]
	v_mfma_f32_16x16x32_bf16 v[46:49], v[148:151], v[210:213], v[46:49]
	v_mfma_f32_16x16x32_bf16 v[42:45], v[162:165], v[210:213], v[42:45]
	v_mfma_f32_16x16x32_bf16 v[30:33], v[148:151], v[218:221], v[30:33]
	v_mfma_f32_16x16x32_bf16 v[26:29], v[162:165], v[218:221], v[26:29]
	v_mfma_f32_16x16x32_bf16 v[14:17], v[148:151], v[226:229], v[14:17]
	v_mfma_f32_16x16x32_bf16 v[10:13], v[162:165], v[226:229], v[10:13]
	v_mfma_f32_16x16x32_bf16 v[54:57], v[166:169], v[184:187], v[54:57]
	v_mfma_f32_16x16x32_bf16 v[50:53], v[174:177], v[184:187], v[50:53]
	v_mfma_f32_16x16x32_bf16 v[38:41], v[166:169], v[196:199], v[38:41]
	v_mfma_f32_16x16x32_bf16 v[34:37], v[174:177], v[196:199], v[34:37]
	v_mfma_f32_16x16x32_bf16 v[22:25], v[166:169], v[214:217], v[22:25]
	v_mfma_f32_16x16x32_bf16 v[18:21], v[174:177], v[214:217], v[18:21]
	v_mfma_f32_16x16x32_bf16 v[6:9], v[166:169], v[222:225], v[6:9]
	v_mfma_f32_16x16x32_bf16 v[2:5], v[174:177], v[222:225], v[2:5]
	v_mfma_f32_16x16x32_bf16 v[54:57], v[170:173], v[188:191], v[54:57]
	v_mfma_f32_16x16x32_bf16 v[50:53], v[178:181], v[188:191], v[50:53]
	v_mfma_f32_16x16x32_bf16 v[38:41], v[170:173], v[210:213], v[38:41]
	v_mfma_f32_16x16x32_bf16 v[34:37], v[178:181], v[210:213], v[34:37]
	v_mfma_f32_16x16x32_bf16 v[22:25], v[170:173], v[218:221], v[22:25]
	v_mfma_f32_16x16x32_bf16 v[18:21], v[178:181], v[218:221], v[18:21]
	v_mfma_f32_16x16x32_bf16 v[6:9], v[170:173], v[226:229], v[6:9]
	v_mfma_f32_16x16x32_bf16 v[2:5], v[178:181], v[226:229], v[2:5]
	s_barrier
	s_add_i32 s28, 0, 0x18000
	v_add_u32_e32 v157, s28, v153
	s_add_i32 s43, 0, 0x1c000
	ds_read_b128 v[130:133], v157
	ds_read_b128 v[148:151], v157 offset:1024
	ds_read_b128 v[158:161], v157 offset:2048
	ds_read_b128 v[162:165], v157 offset:3072
	v_add_u32_e32 v157, s43, v153
	ds_read_b128 v[166:169], v157
	ds_read_b128 v[170:173], v157 offset:1024
	ds_read_b128 v[174:177], v157 offset:2048
	ds_read_b128 v[178:181], v157 offset:3072
	s_add_u32 s52, s52, 0x40000
	s_addc_u32 s53, s53, 0
	s_mov_b32 m0, s59
	v_lshl_add_u64 v[234:235], s[52:53], 0, v[138:139]
	ds_read_b128 v[184:187], v156 offset:32768
	ds_read_b128 v[188:191], v156 offset:33792
	ds_read_b128 v[196:199], v156 offset:34816
	ds_read_b128 v[210:213], v156 offset:35840
	ds_read_b128 v[214:217], v156 offset:36864
	ds_read_b128 v[218:221], v156 offset:37888
	ds_read_b128 v[222:225], v156 offset:38912
	ds_read_b128 v[226:229], v156 offset:39936
	global_load_lds_dwordx4 v[234:235], off
	v_lshl_add_u64 v[234:235], s[52:53], 0, v[136:137]
	s_mov_b32 m0, s60
	s_nop 0
	global_load_lds_dwordx4 v[234:235], off
	s_waitcnt vmcnt(8)
	s_waitcnt lgkmcnt(0)
	s_barrier
	v_mfma_f32_16x16x32_bf16 v[126:129], v[130:133], v[184:187], v[126:129]
	v_mfma_f32_16x16x32_bf16 v[122:125], v[158:161], v[184:187], v[122:125]
	v_mfma_f32_16x16x32_bf16 v[110:113], v[130:133], v[196:199], v[110:113]
	v_mfma_f32_16x16x32_bf16 v[106:109], v[158:161], v[196:199], v[106:109]
	v_mfma_f32_16x16x32_bf16 v[94:97], v[130:133], v[214:217], v[94:97]
	v_mfma_f32_16x16x32_bf16 v[90:93], v[158:161], v[214:217], v[90:93]
	v_mfma_f32_16x16x32_bf16 v[78:81], v[130:133], v[222:225], v[78:81]
	v_mfma_f32_16x16x32_bf16 v[74:77], v[158:161], v[222:225], v[74:77]
	v_mfma_f32_16x16x32_bf16 v[126:129], v[148:151], v[188:191], v[126:129]
	v_mfma_f32_16x16x32_bf16 v[122:125], v[162:165], v[188:191], v[122:125]
	v_mfma_f32_16x16x32_bf16 v[110:113], v[148:151], v[210:213], v[110:113]
	v_mfma_f32_16x16x32_bf16 v[106:109], v[162:165], v[210:213], v[106:109]
	v_mfma_f32_16x16x32_bf16 v[94:97], v[148:151], v[218:221], v[94:97]
	v_mfma_f32_16x16x32_bf16 v[90:93], v[162:165], v[218:221], v[90:93]
	v_mfma_f32_16x16x32_bf16 v[78:81], v[148:151], v[226:229], v[78:81]
	v_mfma_f32_16x16x32_bf16 v[74:77], v[162:165], v[226:229], v[74:77]
	v_mfma_f32_16x16x32_bf16 v[118:121], v[166:169], v[184:187], v[118:121]
	v_mfma_f32_16x16x32_bf16 v[114:117], v[174:177], v[184:187], v[114:117]
	v_mfma_f32_16x16x32_bf16 v[102:105], v[166:169], v[196:199], v[102:105]
	v_mfma_f32_16x16x32_bf16 v[98:101], v[174:177], v[196:199], v[98:101]
	v_mfma_f32_16x16x32_bf16 v[86:89], v[166:169], v[214:217], v[86:89]
	v_mfma_f32_16x16x32_bf16 v[82:85], v[174:177], v[214:217], v[82:85]
	v_mfma_f32_16x16x32_bf16 v[70:73], v[166:169], v[222:225], v[70:73]
	v_mfma_f32_16x16x32_bf16 v[66:69], v[174:177], v[222:225], v[66:69]
	v_mfma_f32_16x16x32_bf16 v[118:121], v[170:173], v[188:191], v[118:121]
	v_mfma_f32_16x16x32_bf16 v[114:117], v[178:181], v[188:191], v[114:117]
	v_mfma_f32_16x16x32_bf16 v[102:105], v[170:173], v[210:213], v[102:105]
	v_mfma_f32_16x16x32_bf16 v[98:101], v[178:181], v[210:213], v[98:101]
	v_mfma_f32_16x16x32_bf16 v[86:89], v[170:173], v[218:221], v[86:89]
	v_mfma_f32_16x16x32_bf16 v[82:85], v[178:181], v[218:221], v[82:85]
	v_mfma_f32_16x16x32_bf16 v[70:73], v[170:173], v[226:229], v[70:73]
	v_mfma_f32_16x16x32_bf16 v[66:69], v[178:181], v[226:229], v[66:69]
	s_barrier
	s_add_i32 s28, s28, s17
	v_lshl_add_u64 v[192:193], v[192:193], 0, s[22:23]
	s_mov_b32 m0, s28
	ds_read_b128 v[184:187], v156 offset:49152
	ds_read_b128 v[188:191], v156 offset:50176
	ds_read_b128 v[196:199], v156 offset:51200
	ds_read_b128 v[210:213], v156 offset:52224
	ds_read_b128 v[214:217], v156 offset:53248
	ds_read_b128 v[218:221], v156 offset:54272
	ds_read_b128 v[222:225], v156 offset:55296
	ds_read_b128 v[226:229], v156 offset:56320
	global_load_lds_dwordx4 v[192:193], off
	s_add_i32 m0, s28, 0x2000
	s_add_u32 s36, s36, 0x40080
	v_lshl_add_u64 v[192:193], v[202:203], 0, s[22:23]
	s_addc_u32 s37, s37, 0
	s_add_i32 s28, s43, s17
	global_load_lds_dwordx4 v[192:193], off
	v_lshl_add_u64 v[192:193], s[36:37], 0, v[0:1]
	s_mov_b32 m0, s28
	s_nop 0
	global_load_lds_dwordx4 v[192:193], off
	v_lshl_add_u64 v[192:193], s[36:37], 0, v[134:135]
	s_add_i32 m0, s28, 0x2000
	s_nop 0
	global_load_lds_dwordx4 v[192:193], off
	v_lshl_add_u64 v[192:193], v[230:231], 0, s[22:23]
	s_mov_b32 m0, s62
	s_nop 0
	global_load_lds_dwordx4 v[192:193], off
	v_lshl_add_u64 v[192:193], v[232:233], 0, s[22:23]
	s_mov_b32 m0, s63
	s_nop 0
	global_load_lds_dwordx4 v[192:193], off
	s_waitcnt vmcnt(8)
	s_waitcnt lgkmcnt(0)
	s_barrier
	v_mfma_f32_16x16x32_bf16 v[62:65], v[130:133], v[184:187], v[62:65]
	v_mfma_f32_16x16x32_bf16 v[58:61], v[158:161], v[184:187], v[58:61]
	v_mfma_f32_16x16x32_bf16 v[46:49], v[130:133], v[196:199], v[46:49]
	v_mfma_f32_16x16x32_bf16 v[42:45], v[158:161], v[196:199], v[42:45]
	v_mfma_f32_16x16x32_bf16 v[30:33], v[130:133], v[214:217], v[30:33]
	v_mfma_f32_16x16x32_bf16 v[26:29], v[158:161], v[214:217], v[26:29]
	v_mfma_f32_16x16x32_bf16 v[14:17], v[130:133], v[222:225], v[14:17]
	v_mfma_f32_16x16x32_bf16 v[10:13], v[158:161], v[222:225], v[10:13]
	v_mfma_f32_16x16x32_bf16 v[62:65], v[148:151], v[188:191], v[62:65]
	v_mfma_f32_16x16x32_bf16 v[58:61], v[162:165], v[188:191], v[58:61]
	v_mfma_f32_16x16x32_bf16 v[46:49], v[148:151], v[210:213], v[46:49]
	v_mfma_f32_16x16x32_bf16 v[42:45], v[162:165], v[210:213], v[42:45]
	v_mfma_f32_16x16x32_bf16 v[30:33], v[148:151], v[218:221], v[30:33]
	v_mfma_f32_16x16x32_bf16 v[26:29], v[162:165], v[218:221], v[26:29]
	v_mfma_f32_16x16x32_bf16 v[14:17], v[148:151], v[226:229], v[14:17]
	v_mfma_f32_16x16x32_bf16 v[10:13], v[162:165], v[226:229], v[10:13]
	v_mfma_f32_16x16x32_bf16 v[54:57], v[166:169], v[184:187], v[54:57]
	v_mfma_f32_16x16x32_bf16 v[50:53], v[174:177], v[184:187], v[50:53]
	v_mfma_f32_16x16x32_bf16 v[38:41], v[166:169], v[196:199], v[38:41]
	v_mfma_f32_16x16x32_bf16 v[34:37], v[174:177], v[196:199], v[34:37]
	v_mfma_f32_16x16x32_bf16 v[22:25], v[166:169], v[214:217], v[22:25]
	v_mfma_f32_16x16x32_bf16 v[18:21], v[174:177], v[214:217], v[18:21]
	v_mfma_f32_16x16x32_bf16 v[6:9], v[166:169], v[222:225], v[6:9]
	v_mfma_f32_16x16x32_bf16 v[2:5], v[174:177], v[222:225], v[2:5]
	v_mfma_f32_16x16x32_bf16 v[54:57], v[170:173], v[188:191], v[54:57]
	v_mfma_f32_16x16x32_bf16 v[50:53], v[178:181], v[188:191], v[50:53]
	v_mfma_f32_16x16x32_bf16 v[38:41], v[170:173], v[210:213], v[38:41]
	v_mfma_f32_16x16x32_bf16 v[34:37], v[178:181], v[210:213], v[34:37]
	v_mfma_f32_16x16x32_bf16 v[22:25], v[170:173], v[218:221], v[22:25]
	v_mfma_f32_16x16x32_bf16 v[18:21], v[178:181], v[218:221], v[18:21]
	v_mfma_f32_16x16x32_bf16 v[6:9], v[170:173], v[226:229], v[6:9]
	v_mfma_f32_16x16x32_bf16 v[2:5], v[178:181], v[226:229], v[2:5]
	s_barrier
	s_add_i32 s26, s26, 2
	s_add_u32 s30, s30, 0x100
	s_addc_u32 s31, s31, 0
	s_add_u32 s24, s24, 0x100
	s_addc_u32 s25, s25, 0
	s_cmp_gt_u32 s26, 13
	s_cbranch_scc0 .LBB0_214
	s_setprio 0
	s_and_b64 vcc, exec, s[34:35]
	s_cbranch_vccz .LBB0_227
	s_barrier
	v_lshl_add_u32 v148, s12, 8, v152
	s_cmp_lt_i32 s74, s64
	s_mov_b64 s[12:13], -1
	s_cbranch_scc0 .LBB0_228

.Lsprio_1:
.LBB0_695:
	s_add_u32 s30, s12, 0xfffc0080
	s_addc_u32 s31, s13, -1
	s_add_i32 s45, 0, 0x10000
	s_cmp_eq_u32 s35, 12
	s_cselect_b32 s37, s3, s31
	s_cselect_b32 s36, s16, s30
	s_cselect_b32 s31, s24, s28
	s_cselect_b32 s30, s25, s26
	s_add_i32 s59, 0, 0x14000
	v_add_u32_e32 v156, s45, v145
	v_add_u32_e32 v172, s59, v145
	ds_read_b128 v[140:143], v156
	ds_read_b128 v[148:151], v156 offset:1024
	ds_read_b128 v[152:155], v156 offset:2048
	ds_read_b128 v[156:159], v156 offset:3072
	ds_read_b128 v[160:163], v172
	ds_read_b128 v[164:167], v172 offset:1024
	ds_read_b128 v[168:171], v172 offset:2048
	ds_read_b128 v[172:175], v172 offset:3072
	v_lshl_add_u64 v[180:181], s[12:13], 0, v[136:137]
	s_add_i32 m0, s51, 0xc000
	ds_read_b128 v[176:179], v147
	ds_read_b128 v[184:187], v147 offset:1024
	ds_read_b128 v[188:191], v147 offset:2048
	ds_read_b128 v[196:199], v147 offset:3072
	ds_read_b128 v[210:213], v147 offset:4096
	ds_read_b128 v[214:217], v147 offset:5120
	ds_read_b128 v[218:221], v147 offset:6144
	ds_read_b128 v[222:225], v147 offset:7168
	global_load_lds_dwordx4 v[180:181], off
	v_lshl_add_u64 v[180:181], s[12:13], 0, v[138:139]
	s_add_i32 m0, s51, 0xe000
	s_nop 0
	global_load_lds_dwordx4 v[180:181], off
	s_waitcnt vmcnt(8)
	s_waitcnt lgkmcnt(0)
	s_barrier
	v_mfma_f32_16x16x32_bf16 v[126:129], v[140:143], v[176:179], v[126:129]
	v_mfma_f32_16x16x32_bf16 v[122:125], v[152:155], v[176:179], v[122:125]
	v_mfma_f32_16x16x32_bf16 v[110:113], v[140:143], v[188:191], v[110:113]
	v_mfma_f32_16x16x32_bf16 v[106:109], v[152:155], v[188:191], v[106:109]
	v_mfma_f32_16x16x32_bf16 v[94:97], v[140:143], v[210:213], v[94:97]
	v_mfma_f32_16x16x32_bf16 v[90:93], v[152:155], v[210:213], v[90:93]
	v_mfma_f32_16x16x32_bf16 v[78:81], v[140:143], v[218:221], v[78:81]
	v_mfma_f32_16x16x32_bf16 v[74:77], v[152:155], v[218:221], v[74:77]
	v_mfma_f32_16x16x32_bf16 v[126:129], v[148:151], v[184:187], v[126:129]
	v_mfma_f32_16x16x32_bf16 v[122:125], v[156:159], v[184:187], v[122:125]
	v_mfma_f32_16x16x32_bf16 v[110:113], v[148:151], v[196:199], v[110:113]
	v_mfma_f32_16x16x32_bf16 v[106:109], v[156:159], v[196:199], v[106:109]
	v_mfma_f32_16x16x32_bf16 v[94:97], v[148:151], v[214:217], v[94:97]
	v_mfma_f32_16x16x32_bf16 v[90:93], v[156:159], v[214:217], v[90:93]
	v_mfma_f32_16x16x32_bf16 v[78:81], v[148:151], v[222:225], v[78:81]
	v_mfma_f32_16x16x32_bf16 v[74:77], v[156:159], v[222:225], v[74:77]
	v_mfma_f32_16x16x32_bf16 v[118:121], v[160:163], v[176:179], v[118:121]
	v_mfma_f32_16x16x32_bf16 v[114:117], v[168:171], v[176:179], v[114:117]
	v_mfma_f32_16x16x32_bf16 v[102:105], v[160:163], v[188:191], v[102:105]
	v_mfma_f32_16x16x32_bf16 v[98:101], v[168:171], v[188:191], v[98:101]
	v_mfma_f32_16x16x32_bf16 v[86:89], v[160:163], v[210:213], v[86:89]
	v_mfma_f32_16x16x32_bf16 v[82:85], v[168:171], v[210:213], v[82:85]
	v_mfma_f32_16x16x32_bf16 v[70:73], v[160:163], v[218:221], v[70:73]
	v_mfma_f32_16x16x32_bf16 v[66:69], v[168:171], v[218:221], v[66:69]
	v_mfma_f32_16x16x32_bf16 v[118:121], v[164:167], v[184:187], v[118:121]
	v_mfma_f32_16x16x32_bf16 v[114:117], v[172:175], v[184:187], v[114:117]
	v_mfma_f32_16x16x32_bf16 v[102:105], v[164:167], v[196:199], v[102:105]
	v_mfma_f32_16x16x32_bf16 v[98:101], v[172:175], v[196:199], v[98:101]
	v_mfma_f32_16x16x32_bf16 v[86:89], v[164:167], v[214:217], v[86:89]
	v_mfma_f32_16x16x32_bf16 v[82:85], v[172:175], v[214:217], v[82:85]
	v_mfma_f32_16x16x32_bf16 v[70:73], v[164:167], v[222:225], v[70:73]
	v_mfma_f32_16x16x32_bf16 v[66:69], v[172:175], v[222:225], v[66:69]
	s_barrier
	s_add_i32 s45, s45, s50
	v_lshl_add_u64 v[180:181], s[30:31], 0, v[0:1]
	s_mov_b32 m0, s45
	ds_read_b128 v[176:179], v147 offset:16384
	ds_read_b128 v[184:187], v147 offset:17408
	ds_read_b128 v[188:191], v147 offset:18432
	ds_read_b128 v[196:199], v147 offset:19456
	ds_read_b128 v[210:213], v147 offset:20480
	ds_read_b128 v[214:217], v147 offset:21504
	ds_read_b128 v[218:221], v147 offset:22528
	ds_read_b128 v[222:225], v147 offset:23552
	global_load_lds_dwordx4 v[180:181], off
	s_add_i32 m0, s45, 0x2000
	s_add_u32 s60, s30, 0x40000
	v_lshl_add_u64 v[192:193], s[30:31], 0, v[130:131]
	s_addc_u32 s61, s31, 0
	s_add_i32 s45, s59, s50
	global_load_lds_dwordx4 v[192:193], off
	v_lshl_add_u64 v[202:203], s[60:61], 0, v[0:1]
	s_mov_b32 m0, s45
	v_lshl_add_u64 v[226:227], s[36:37], 0, v[132:133]
	global_load_lds_dwordx4 v[202:203], off
	v_lshl_add_u64 v[202:203], s[60:61], 0, v[130:131]
	s_add_i32 m0, s45, 0x2000
	s_nop 0
	global_load_lds_dwordx4 v[202:203], off
	v_lshl_add_u64 v[202:203], s[36:37], 0, v[134:135]
	s_mov_b32 m0, s51
	s_nop 0
	global_load_lds_dwordx4 v[202:203], off
	s_mov_b32 m0, s52
	s_nop 0
	global_load_lds_dwordx4 v[226:227], off
	s_waitcnt vmcnt(8)
	s_waitcnt lgkmcnt(0)
	s_barrier
	v_mfma_f32_16x16x32_bf16 v[62:65], v[140:143], v[176:179], v[62:65]
	v_mfma_f32_16x16x32_bf16 v[58:61], v[152:155], v[176:179], v[58:61]
	v_mfma_f32_16x16x32_bf16 v[46:49], v[140:143], v[188:191], v[46:49]
	v_mfma_f32_16x16x32_bf16 v[42:45], v[152:155], v[188:191], v[42:45]
	v_mfma_f32_16x16x32_bf16 v[30:33], v[140:143], v[210:213], v[30:33]
	v_mfma_f32_16x16x32_bf16 v[26:29], v[152:155], v[210:213], v[26:29]
	v_mfma_f32_16x16x32_bf16 v[14:17], v[140:143], v[218:221], v[14:17]
	v_mfma_f32_16x16x32_bf16 v[10:13], v[152:155], v[218:221], v[10:13]
	v_mfma_f32_16x16x32_bf16 v[62:65], v[148:151], v[184:187], v[62:65]
	v_mfma_f32_16x16x32_bf16 v[58:61], v[156:159], v[184:187], v[58:61]
	v_mfma_f32_16x16x32_bf16 v[46:49], v[148:151], v[196:199], v[46:49]
	v_mfma_f32_16x16x32_bf16 v[42:45], v[156:159], v[196:199], v[42:45]
	v_mfma_f32_16x16x32_bf16 v[30:33], v[148:151], v[214:217], v[30:33]
	v_mfma_f32_16x16x32_bf16 v[26:29], v[156:159], v[214:217], v[26:29]
	v_mfma_f32_16x16x32_bf16 v[14:17], v[148:151], v[222:225], v[14:17]
	v_mfma_f32_16x16x32_bf16 v[10:13], v[156:159], v[222:225], v[10:13]
	v_mfma_f32_16x16x32_bf16 v[54:57], v[160:163], v[176:179], v[54:57]
	v_mfma_f32_16x16x32_bf16 v[50:53], v[168:171], v[176:179], v[50:53]
	v_mfma_f32_16x16x32_bf16 v[38:41], v[160:163], v[188:191], v[38:41]
	v_mfma_f32_16x16x32_bf16 v[34:37], v[168:171], v[188:191], v[34:37]
	v_mfma_f32_16x16x32_bf16 v[22:25], v[160:163], v[210:213], v[22:25]
	v_mfma_f32_16x16x32_bf16 v[18:21], v[168:171], v[210:213], v[18:21]
	v_mfma_f32_16x16x32_bf16 v[6:9], v[160:163], v[218:221], v[6:9]
	v_mfma_f32_16x16x32_bf16 v[2:5], v[168:171], v[218:221], v[2:5]
	v_mfma_f32_16x16x32_bf16 v[54:57], v[164:167], v[184:187], v[54:57]
	v_mfma_f32_16x16x32_bf16 v[50:53], v[172:175], v[184:187], v[50:53]
	v_mfma_f32_16x16x32_bf16 v[38:41], v[164:167], v[196:199], v[38:41]
	v_mfma_f32_16x16x32_bf16 v[34:37], v[172:175], v[196:199], v[34:37]
	v_mfma_f32_16x16x32_bf16 v[22:25], v[164:167], v[214:217], v[22:25]
	v_mfma_f32_16x16x32_bf16 v[18:21], v[172:175], v[214:217], v[18:21]
	v_mfma_f32_16x16x32_bf16 v[6:9], v[164:167], v[222:225], v[6:9]
	v_mfma_f32_16x16x32_bf16 v[2:5], v[172:175], v[222:225], v[2:5]
	s_barrier
	s_add_i32 s45, 0, 0x18000
	s_add_i32 s59, 0, 0x1c000
	v_add_u32_e32 v156, s45, v145
	v_add_u32_e32 v172, s59, v145
	ds_read_b128 v[140:143], v156
	ds_read_b128 v[148:151], v156 offset:1024
	ds_read_b128 v[152:155], v156 offset:2048
	ds_read_b128 v[156:159], v156 offset:3072
	ds_read_b128 v[160:163], v172
	ds_read_b128 v[164:167], v172 offset:1024
	ds_read_b128 v[168:171], v172 offset:2048
	ds_read_b128 v[172:175], v172 offset:3072
	s_add_u32 s36, s36, 0x40000
	s_addc_u32 s37, s37, 0
	s_mov_b32 m0, s53
	v_lshl_add_u64 v[228:229], s[36:37], 0, v[134:135]
	ds_read_b128 v[176:179], v147 offset:32768
	ds_read_b128 v[184:187], v147 offset:33792
	ds_read_b128 v[188:191], v147 offset:34816
	ds_read_b128 v[196:199], v147 offset:35840
	ds_read_b128 v[210:213], v147 offset:36864
	ds_read_b128 v[214:217], v147 offset:37888
	ds_read_b128 v[218:221], v147 offset:38912
	ds_read_b128 v[222:225], v147 offset:39936
	global_load_lds_dwordx4 v[228:229], off
	v_lshl_add_u64 v[228:229], s[36:37], 0, v[132:133]
	s_mov_b32 m0, s54
	s_nop 0
	global_load_lds_dwordx4 v[228:229], off
	s_waitcnt vmcnt(8)
	s_waitcnt lgkmcnt(0)
	s_barrier
	v_mfma_f32_16x16x32_bf16 v[126:129], v[140:143], v[176:179], v[126:129]
	v_mfma_f32_16x16x32_bf16 v[122:125], v[152:155], v[176:179], v[122:125]
	v_mfma_f32_16x16x32_bf16 v[110:113], v[140:143], v[188:191], v[110:113]
	v_mfma_f32_16x16x32_bf16 v[106:109], v[152:155], v[188:191], v[106:109]
	v_mfma_f32_16x16x32_bf16 v[94:97], v[140:143], v[210:213], v[94:97]
	v_mfma_f32_16x16x32_bf16 v[90:93], v[152:155], v[210:213], v[90:93]
	v_mfma_f32_16x16x32_bf16 v[78:81], v[140:143], v[218:221], v[78:81]
	v_mfma_f32_16x16x32_bf16 v[74:77], v[152:155], v[218:221], v[74:77]
	v_mfma_f32_16x16x32_bf16 v[126:129], v[148:151], v[184:187], v[126:129]
	v_mfma_f32_16x16x32_bf16 v[122:125], v[156:159], v[184:187], v[122:125]
	v_mfma_f32_16x16x32_bf16 v[110:113], v[148:151], v[196:199], v[110:113]
	v_mfma_f32_16x16x32_bf16 v[106:109], v[156:159], v[196:199], v[106:109]
	v_mfma_f32_16x16x32_bf16 v[94:97], v[148:151], v[214:217], v[94:97]
	v_mfma_f32_16x16x32_bf16 v[90:93], v[156:159], v[214:217], v[90:93]
	v_mfma_f32_16x16x32_bf16 v[78:81], v[148:151], v[222:225], v[78:81]
	v_mfma_f32_16x16x32_bf16 v[74:77], v[156:159], v[222:225], v[74:77]
	v_mfma_f32_16x16x32_bf16 v[118:121], v[160:163], v[176:179], v[118:121]
	v_mfma_f32_16x16x32_bf16 v[114:117], v[168:171], v[176:179], v[114:117]
	v_mfma_f32_16x16x32_bf16 v[102:105], v[160:163], v[188:191], v[102:105]
	v_mfma_f32_16x16x32_bf16 v[98:101], v[168:171], v[188:191], v[98:101]
	v_mfma_f32_16x16x32_bf16 v[86:89], v[160:163], v[210:213], v[86:89]
	v_mfma_f32_16x16x32_bf16 v[82:85], v[168:171], v[210:213], v[82:85]
	v_mfma_f32_16x16x32_bf16 v[70:73], v[160:163], v[218:221], v[70:73]
	v_mfma_f32_16x16x32_bf16 v[66:69], v[168:171], v[218:221], v[66:69]
	v_mfma_f32_16x16x32_bf16 v[118:121], v[164:167], v[184:187], v[118:121]
	v_mfma_f32_16x16x32_bf16 v[114:117], v[172:175], v[184:187], v[114:117]
	v_mfma_f32_16x16x32_bf16 v[102:105], v[164:167], v[196:199], v[102:105]
	v_mfma_f32_16x16x32_bf16 v[98:101], v[172:175], v[196:199], v[98:101]
	v_mfma_f32_16x16x32_bf16 v[86:89], v[164:167], v[214:217], v[86:89]
	v_mfma_f32_16x16x32_bf16 v[82:85], v[172:175], v[214:217], v[82:85]
	v_mfma_f32_16x16x32_bf16 v[70:73], v[164:167], v[222:225], v[70:73]
	v_mfma_f32_16x16x32_bf16 v[66:69], v[172:175], v[222:225], v[66:69]
	s_barrier
	s_add_i32 s36, s45, s50
	v_lshl_add_u64 v[180:181], v[180:181], 0, s[22:23]
	s_mov_b32 m0, s36
	ds_read_b128 v[176:179], v147 offset:49152
	ds_read_b128 v[184:187], v147 offset:50176
	ds_read_b128 v[188:191], v147 offset:51200
	ds_read_b128 v[196:199], v147 offset:52224
	ds_read_b128 v[210:213], v147 offset:53248
	ds_read_b128 v[214:217], v147 offset:54272
	ds_read_b128 v[218:221], v147 offset:55296
	ds_read_b128 v[222:225], v147 offset:56320
	global_load_lds_dwordx4 v[180:181], off
	s_add_i32 m0, s36, 0x2000
	s_add_u32 s30, s30, 0x40080
	v_lshl_add_u64 v[180:181], v[192:193], 0, s[22:23]
	s_addc_u32 s31, s31, 0
	s_add_i32 s36, s59, s50
	global_load_lds_dwordx4 v[180:181], off
	v_lshl_add_u64 v[180:181], s[30:31], 0, v[0:1]
	s_mov_b32 m0, s36
	s_nop 0
	global_load_lds_dwordx4 v[180:181], off
	v_lshl_add_u64 v[180:181], s[30:31], 0, v[130:131]
	s_add_i32 m0, s36, 0x2000
	s_nop 0
	global_load_lds_dwordx4 v[180:181], off
	v_lshl_add_u64 v[180:181], v[202:203], 0, s[22:23]
	s_mov_b32 m0, s56
	s_nop 0
	global_load_lds_dwordx4 v[180:181], off
	v_lshl_add_u64 v[180:181], v[226:227], 0, s[22:23]
	s_mov_b32 m0, s57
	s_nop 0
	global_load_lds_dwordx4 v[180:181], off
	s_waitcnt vmcnt(8)
	s_waitcnt lgkmcnt(0)
	s_barrier
	v_mfma_f32_16x16x32_bf16 v[62:65], v[140:143], v[176:179], v[62:65]
	v_mfma_f32_16x16x32_bf16 v[58:61], v[152:155], v[176:179], v[58:61]
	v_mfma_f32_16x16x32_bf16 v[46:49], v[140:143], v[188:191], v[46:49]
	v_mfma_f32_16x16x32_bf16 v[42:45], v[152:155], v[188:191], v[42:45]
	v_mfma_f32_16x16x32_bf16 v[30:33], v[140:143], v[210:213], v[30:33]
	v_mfma_f32_16x16x32_bf16 v[26:29], v[152:155], v[210:213], v[26:29]
	v_mfma_f32_16x16x32_bf16 v[14:17], v[140:143], v[218:221], v[14:17]
	v_mfma_f32_16x16x32_bf16 v[10:13], v[152:155], v[218:221], v[10:13]
	v_mfma_f32_16x16x32_bf16 v[62:65], v[148:151], v[184:187], v[62:65]
	v_mfma_f32_16x16x32_bf16 v[58:61], v[156:159], v[184:187], v[58:61]
	v_mfma_f32_16x16x32_bf16 v[46:49], v[148:151], v[196:199], v[46:49]
	v_mfma_f32_16x16x32_bf16 v[42:45], v[156:159], v[196:199], v[42:45]
	v_mfma_f32_16x16x32_bf16 v[30:33], v[148:151], v[214:217], v[30:33]
	v_mfma_f32_16x16x32_bf16 v[26:29], v[156:159], v[214:217], v[26:29]
	v_mfma_f32_16x16x32_bf16 v[14:17], v[148:151], v[222:225], v[14:17]
	v_mfma_f32_16x16x32_bf16 v[10:13], v[156:159], v[222:225], v[10:13]
	v_mfma_f32_16x16x32_bf16 v[54:57], v[160:163], v[176:179], v[54:57]
	v_mfma_f32_16x16x32_bf16 v[50:53], v[168:171], v[176:179], v[50:53]
	v_mfma_f32_16x16x32_bf16 v[38:41], v[160:163], v[188:191], v[38:41]
	v_mfma_f32_16x16x32_bf16 v[34:37], v[168:171], v[188:191], v[34:37]
	v_mfma_f32_16x16x32_bf16 v[22:25], v[160:163], v[210:213], v[22:25]
	v_mfma_f32_16x16x32_bf16 v[18:21], v[168:171], v[210:213], v[18:21]
	v_mfma_f32_16x16x32_bf16 v[6:9], v[160:163], v[218:221], v[6:9]
	v_mfma_f32_16x16x32_bf16 v[2:5], v[168:171], v[218:221], v[2:5]
	v_mfma_f32_16x16x32_bf16 v[54:57], v[164:167], v[184:187], v[54:57]
	v_mfma_f32_16x16x32_bf16 v[50:53], v[172:175], v[184:187], v[50:53]
	v_mfma_f32_16x16x32_bf16 v[38:41], v[164:167], v[196:199], v[38:41]
	v_mfma_f32_16x16x32_bf16 v[34:37], v[172:175], v[196:199], v[34:37]
	v_mfma_f32_16x16x32_bf16 v[22:25], v[164:167], v[214:217], v[22:25]
	v_mfma_f32_16x16x32_bf16 v[18:21], v[172:175], v[214:217], v[18:21]
	v_mfma_f32_16x16x32_bf16 v[6:9], v[164:167], v[222:225], v[6:9]
	v_mfma_f32_16x16x32_bf16 v[2:5], v[172:175], v[222:225], v[2:5]
	s_barrier
	s_add_i32 s35, s35, 2
	s_add_u32 s12, s12, 0x100
	s_addc_u32 s13, s13, 0
	s_add_u32 s26, s26, 0x100
	s_addc_u32 s28, s28, 0
	s_cmp_gt_u32 s35, 13
	s_cbranch_scc0 .LBB0_695
	s_setprio 0
	s_and_b64 vcc, exec, s[20:21]
	s_cbranch_vccz .LBB0_698
	s_barrier

.Lsprio_2:
.LBB0_792:
	s_add_u32 s36, s34, 0xfffc0080
	s_addc_u32 s37, s35, -1
	s_add_i32 s51, 0, 0x10000
	s_cmp_eq_u32 s50, 12
	s_cselect_b32 s41, s15, s37
	s_cselect_b32 s40, s46, s36
	v_add_u32_e32 v149, s51, v145
	s_cselect_b32 s37, s13, s49
	s_cselect_b32 s36, s47, s48
	s_add_i32 s54, 0, 0x14000
	ds_read_b128 v[140:143], v149
	ds_read_b128 v[150:153], v149 offset:1024
	ds_read_b128 v[154:157], v149 offset:2048
	ds_read_b128 v[158:161], v149 offset:3072
	v_add_u32_e32 v149, s54, v145
	ds_read_b128 v[162:165], v149
	ds_read_b128 v[166:169], v149 offset:1024
	ds_read_b128 v[170:173], v149 offset:2048
	ds_read_b128 v[174:177], v149 offset:3072
	v_lshl_add_u64 v[192:193], s[34:35], 0, v[136:137]
	s_add_i32 m0, s18, 0xc000
	ds_read_b128 v[178:181], v148
	ds_read_b128 v[184:187], v148 offset:1024
	ds_read_b128 v[188:191], v148 offset:2048
	ds_read_b128 v[196:199], v148 offset:3072
	ds_read_b128 v[210:213], v148 offset:4096
	ds_read_b128 v[214:217], v148 offset:5120
	ds_read_b128 v[218:221], v148 offset:6144
	ds_read_b128 v[222:225], v148 offset:7168
	global_load_lds_dwordx4 v[192:193], off
	v_lshl_add_u64 v[192:193], s[34:35], 0, v[138:139]
	s_add_i32 m0, s18, 0xe000
	s_nop 0
	global_load_lds_dwordx4 v[192:193], off
	s_waitcnt vmcnt(8)
	s_waitcnt lgkmcnt(0)
	s_barrier
	v_mfma_f32_16x16x32_bf16 v[126:129], v[140:143], v[178:181], v[126:129]
	v_mfma_f32_16x16x32_bf16 v[122:125], v[154:157], v[178:181], v[122:125]
	v_mfma_f32_16x16x32_bf16 v[110:113], v[140:143], v[188:191], v[110:113]
	v_mfma_f32_16x16x32_bf16 v[106:109], v[154:157], v[188:191], v[106:109]
	v_mfma_f32_16x16x32_bf16 v[94:97], v[140:143], v[210:213], v[94:97]
	v_mfma_f32_16x16x32_bf16 v[90:93], v[154:157], v[210:213], v[90:93]
	v_mfma_f32_16x16x32_bf16 v[78:81], v[140:143], v[218:221], v[78:81]
	v_mfma_f32_16x16x32_bf16 v[74:77], v[154:157], v[218:221], v[74:77]
	v_mfma_f32_16x16x32_bf16 v[126:129], v[150:153], v[184:187], v[126:129]
	v_mfma_f32_16x16x32_bf16 v[122:125], v[158:161], v[184:187], v[122:125]
	v_mfma_f32_16x16x32_bf16 v[110:113], v[150:153], v[196:199], v[110:113]
	v_mfma_f32_16x16x32_bf16 v[106:109], v[158:161], v[196:199], v[106:109]
	v_mfma_f32_16x16x32_bf16 v[94:97], v[150:153], v[214:217], v[94:97]
	v_mfma_f32_16x16x32_bf16 v[90:93], v[158:161], v[214:217], v[90:93]
	v_mfma_f32_16x16x32_bf16 v[78:81], v[150:153], v[222:225], v[78:81]
	v_mfma_f32_16x16x32_bf16 v[74:77], v[158:161], v[222:225], v[74:77]
	v_mfma_f32_16x16x32_bf16 v[118:121], v[162:165], v[178:181], v[118:121]
	v_mfma_f32_16x16x32_bf16 v[114:117], v[170:173], v[178:181], v[114:117]
	v_mfma_f32_16x16x32_bf16 v[102:105], v[162:165], v[188:191], v[102:105]
	v_mfma_f32_16x16x32_bf16 v[98:101], v[170:173], v[188:191], v[98:101]
	v_mfma_f32_16x16x32_bf16 v[86:89], v[162:165], v[210:213], v[86:89]
	v_mfma_f32_16x16x32_bf16 v[82:85], v[170:173], v[210:213], v[82:85]
	v_mfma_f32_16x16x32_bf16 v[70:73], v[162:165], v[218:221], v[70:73]
	v_mfma_f32_16x16x32_bf16 v[66:69], v[170:173], v[218:221], v[66:69]
	v_mfma_f32_16x16x32_bf16 v[118:121], v[166:169], v[184:187], v[118:121]
	v_mfma_f32_16x16x32_bf16 v[114:117], v[174:177], v[184:187], v[114:117]
	v_mfma_f32_16x16x32_bf16 v[102:105], v[166:169], v[196:199], v[102:105]
	v_mfma_f32_16x16x32_bf16 v[98:101], v[174:177], v[196:199], v[98:101]
	v_mfma_f32_16x16x32_bf16 v[86:89], v[166:169], v[214:217], v[86:89]
	v_mfma_f32_16x16x32_bf16 v[82:85], v[174:177], v[214:217], v[82:85]
	v_mfma_f32_16x16x32_bf16 v[70:73], v[166:169], v[222:225], v[70:73]
	v_mfma_f32_16x16x32_bf16 v[66:69], v[174:177], v[222:225], v[66:69]
	s_barrier
	s_add_i32 s51, s51, s0
	v_lshl_add_u64 v[192:193], s[36:37], 0, v[0:1]
	s_mov_b32 m0, s51
	ds_read_b128 v[178:181], v148 offset:16384
	ds_read_b128 v[184:187], v148 offset:17408
	ds_read_b128 v[188:191], v148 offset:18432
	ds_read_b128 v[196:199], v148 offset:19456
	ds_read_b128 v[210:213], v148 offset:20480
	ds_read_b128 v[214:217], v148 offset:21504
	ds_read_b128 v[218:221], v148 offset:22528
	ds_read_b128 v[222:225], v148 offset:23552
	global_load_lds_dwordx4 v[192:193], off
	s_add_i32 m0, s51, 0x2000
	s_add_u32 s52, s36, 0x40000
	v_lshl_add_u64 v[202:203], s[36:37], 0, v[130:131]
	s_addc_u32 s53, s37, 0
	s_add_i32 s51, s54, s0
	global_load_lds_dwordx4 v[202:203], off
	v_lshl_add_u64 v[226:227], s[52:53], 0, v[0:1]
	s_mov_b32 m0, s51
	v_lshl_add_u64 v[228:229], s[40:41], 0, v[132:133]
	global_load_lds_dwordx4 v[226:227], off
	v_lshl_add_u64 v[226:227], s[52:53], 0, v[130:131]
	s_add_i32 m0, s51, 0x2000
	s_nop 0
	global_load_lds_dwordx4 v[226:227], off
	v_lshl_add_u64 v[226:227], s[40:41], 0, v[134:135]
	s_mov_b32 m0, s18
	s_nop 0
	global_load_lds_dwordx4 v[226:227], off
	s_mov_b32 m0, s19
	s_nop 0
	global_load_lds_dwordx4 v[228:229], off
	s_waitcnt vmcnt(8)
	s_waitcnt lgkmcnt(0)
	s_barrier
	v_mfma_f32_16x16x32_bf16 v[62:65], v[140:143], v[178:181], v[62:65]
	v_mfma_f32_16x16x32_bf16 v[58:61], v[154:157], v[178:181], v[58:61]
	v_mfma_f32_16x16x32_bf16 v[46:49], v[140:143], v[188:191], v[46:49]
	v_mfma_f32_16x16x32_bf16 v[42:45], v[154:157], v[188:191], v[42:45]
	v_mfma_f32_16x16x32_bf16 v[30:33], v[140:143], v[210:213], v[30:33]
	v_mfma_f32_16x16x32_bf16 v[26:29], v[154:157], v[210:213], v[26:29]
	v_mfma_f32_16x16x32_bf16 v[14:17], v[140:143], v[218:221], v[14:17]
	v_mfma_f32_16x16x32_bf16 v[10:13], v[154:157], v[218:221], v[10:13]
	v_mfma_f32_16x16x32_bf16 v[62:65], v[150:153], v[184:187], v[62:65]
	v_mfma_f32_16x16x32_bf16 v[58:61], v[158:161], v[184:187], v[58:61]
	v_mfma_f32_16x16x32_bf16 v[46:49], v[150:153], v[196:199], v[46:49]
	v_mfma_f32_16x16x32_bf16 v[42:45], v[158:161], v[196:199], v[42:45]
	v_mfma_f32_16x16x32_bf16 v[30:33], v[150:153], v[214:217], v[30:33]
	v_mfma_f32_16x16x32_bf16 v[26:29], v[158:161], v[214:217], v[26:29]
	v_mfma_f32_16x16x32_bf16 v[14:17], v[150:153], v[222:225], v[14:17]
	v_mfma_f32_16x16x32_bf16 v[10:13], v[158:161], v[222:225], v[10:13]
	v_mfma_f32_16x16x32_bf16 v[54:57], v[162:165], v[178:181], v[54:57]
	v_mfma_f32_16x16x32_bf16 v[50:53], v[170:173], v[178:181], v[50:53]
	v_mfma_f32_16x16x32_bf16 v[38:41], v[162:165], v[188:191], v[38:41]
	v_mfma_f32_16x16x32_bf16 v[34:37], v[170:173], v[188:191], v[34:37]
	v_mfma_f32_16x16x32_bf16 v[22:25], v[162:165], v[210:213], v[22:25]
	v_mfma_f32_16x16x32_bf16 v[18:21], v[170:173], v[210:213], v[18:21]
	v_mfma_f32_16x16x32_bf16 v[6:9], v[162:165], v[218:221], v[6:9]
	v_mfma_f32_16x16x32_bf16 v[2:5], v[170:173], v[218:221], v[2:5]
	v_mfma_f32_16x16x32_bf16 v[54:57], v[166:169], v[184:187], v[54:57]
	v_mfma_f32_16x16x32_bf16 v[50:53], v[174:177], v[184:187], v[50:53]
	v_mfma_f32_16x16x32_bf16 v[38:41], v[166:169], v[196:199], v[38:41]
	v_mfma_f32_16x16x32_bf16 v[34:37], v[174:177], v[196:199], v[34:37]
	v_mfma_f32_16x16x32_bf16 v[22:25], v[166:169], v[214:217], v[22:25]
	v_mfma_f32_16x16x32_bf16 v[18:21], v[174:177], v[214:217], v[18:21]
	v_mfma_f32_16x16x32_bf16 v[6:9], v[166:169], v[222:225], v[6:9]
	v_mfma_f32_16x16x32_bf16 v[2:5], v[174:177], v[222:225], v[2:5]
	s_barrier
	s_add_i32 s51, 0, 0x18000
	v_add_u32_e32 v149, s51, v145
	s_add_i32 s52, 0, 0x1c000
	ds_read_b128 v[140:143], v149
	ds_read_b128 v[150:153], v149 offset:1024
	ds_read_b128 v[154:157], v149 offset:2048
	ds_read_b128 v[158:161], v149 offset:3072
	v_add_u32_e32 v149, s52, v145
	ds_read_b128 v[162:165], v149
	ds_read_b128 v[166:169], v149 offset:1024
	ds_read_b128 v[170:173], v149 offset:2048
	ds_read_b128 v[174:177], v149 offset:3072
	s_add_u32 s40, s40, 0x40000
	s_addc_u32 s41, s41, 0
	s_mov_b32 m0, s24
	v_lshl_add_u64 v[230:231], s[40:41], 0, v[134:135]
	ds_read_b128 v[178:181], v148 offset:32768
	ds_read_b128 v[184:187], v148 offset:33792
	ds_read_b128 v[188:191], v148 offset:34816
	ds_read_b128 v[196:199], v148 offset:35840
	ds_read_b128 v[210:213], v148 offset:36864
	ds_read_b128 v[214:217], v148 offset:37888
	ds_read_b128 v[218:221], v148 offset:38912
	ds_read_b128 v[222:225], v148 offset:39936
	global_load_lds_dwordx4 v[230:231], off
	v_lshl_add_u64 v[230:231], s[40:41], 0, v[132:133]
	s_mov_b32 m0, s25
	s_nop 0
	global_load_lds_dwordx4 v[230:231], off
	s_waitcnt vmcnt(8)
	s_waitcnt lgkmcnt(0)
	s_barrier
	v_mfma_f32_16x16x32_bf16 v[126:129], v[140:143], v[178:181], v[126:129]
	v_mfma_f32_16x16x32_bf16 v[122:125], v[154:157], v[178:181], v[122:125]
	v_mfma_f32_16x16x32_bf16 v[110:113], v[140:143], v[188:191], v[110:113]
	v_mfma_f32_16x16x32_bf16 v[106:109], v[154:157], v[188:191], v[106:109]
	v_mfma_f32_16x16x32_bf16 v[94:97], v[140:143], v[210:213], v[94:97]
	v_mfma_f32_16x16x32_bf16 v[90:93], v[154:157], v[210:213], v[90:93]
	v_mfma_f32_16x16x32_bf16 v[78:81], v[140:143], v[218:221], v[78:81]
	v_mfma_f32_16x16x32_bf16 v[74:77], v[154:157], v[218:221], v[74:77]
	v_mfma_f32_16x16x32_bf16 v[126:129], v[150:153], v[184:187], v[126:129]
	v_mfma_f32_16x16x32_bf16 v[122:125], v[158:161], v[184:187], v[122:125]
	v_mfma_f32_16x16x32_bf16 v[110:113], v[150:153], v[196:199], v[110:113]
	v_mfma_f32_16x16x32_bf16 v[106:109], v[158:161], v[196:199], v[106:109]
	v_mfma_f32_16x16x32_bf16 v[94:97], v[150:153], v[214:217], v[94:97]
	v_mfma_f32_16x16x32_bf16 v[90:93], v[158:161], v[214:217], v[90:93]
	v_mfma_f32_16x16x32_bf16 v[78:81], v[150:153], v[222:225], v[78:81]
	v_mfma_f32_16x16x32_bf16 v[74:77], v[158:161], v[222:225], v[74:77]
	v_mfma_f32_16x16x32_bf16 v[118:121], v[162:165], v[178:181], v[118:121]
	v_mfma_f32_16x16x32_bf16 v[114:117], v[170:173], v[178:181], v[114:117]
	v_mfma_f32_16x16x32_bf16 v[102:105], v[162:165], v[188:191], v[102:105]
	v_mfma_f32_16x16x32_bf16 v[98:101], v[170:173], v[188:191], v[98:101]
	v_mfma_f32_16x16x32_bf16 v[86:89], v[162:165], v[210:213], v[86:89]
	v_mfma_f32_16x16x32_bf16 v[82:85], v[170:173], v[210:213], v[82:85]
	v_mfma_f32_16x16x32_bf16 v[70:73], v[162:165], v[218:221], v[70:73]
	v_mfma_f32_16x16x32_bf16 v[66:69], v[170:173], v[218:221], v[66:69]
	v_mfma_f32_16x16x32_bf16 v[118:121], v[166:169], v[184:187], v[118:121]
	v_mfma_f32_16x16x32_bf16 v[114:117], v[174:177], v[184:187], v[114:117]
	v_mfma_f32_16x16x32_bf16 v[102:105], v[166:169], v[196:199], v[102:105]
	v_mfma_f32_16x16x32_bf16 v[98:101], v[174:177], v[196:199], v[98:101]
	v_mfma_f32_16x16x32_bf16 v[86:89], v[166:169], v[214:217], v[86:89]
	v_mfma_f32_16x16x32_bf16 v[82:85], v[174:177], v[214:217], v[82:85]
	v_mfma_f32_16x16x32_bf16 v[70:73], v[166:169], v[222:225], v[70:73]
	v_mfma_f32_16x16x32_bf16 v[66:69], v[174:177], v[222:225], v[66:69]
	s_barrier
	s_add_i32 s40, s51, s0
	v_lshl_add_u64 v[192:193], v[192:193], 0, s[22:23]
	s_mov_b32 m0, s40
	ds_read_b128 v[178:181], v148 offset:49152
	ds_read_b128 v[184:187], v148 offset:50176
	ds_read_b128 v[188:191], v148 offset:51200
	ds_read_b128 v[196:199], v148 offset:52224
	ds_read_b128 v[210:213], v148 offset:53248
	ds_read_b128 v[214:217], v148 offset:54272
	ds_read_b128 v[218:221], v148 offset:55296
	ds_read_b128 v[222:225], v148 offset:56320
	global_load_lds_dwordx4 v[192:193], off
	s_add_i32 m0, s40, 0x2000
	s_add_u32 s36, s36, 0x40080
	v_lshl_add_u64 v[192:193], v[202:203], 0, s[22:23]
	s_addc_u32 s37, s37, 0
	s_add_i32 s40, s52, s0
	global_load_lds_dwordx4 v[192:193], off
	v_lshl_add_u64 v[192:193], s[36:37], 0, v[0:1]
	s_mov_b32 m0, s40
	s_nop 0
	global_load_lds_dwordx4 v[192:193], off
	v_lshl_add_u64 v[192:193], s[36:37], 0, v[130:131]
	s_add_i32 m0, s40, 0x2000
	s_nop 0
	global_load_lds_dwordx4 v[192:193], off
	v_lshl_add_u64 v[192:193], v[226:227], 0, s[22:23]
	s_mov_b32 m0, s26
	s_nop 0
	global_load_lds_dwordx4 v[192:193], off
	v_lshl_add_u64 v[192:193], v[228:229], 0, s[22:23]
	s_mov_b32 m0, s28
	s_nop 0
	global_load_lds_dwordx4 v[192:193], off
	s_waitcnt vmcnt(8)
	s_waitcnt lgkmcnt(0)
	s_barrier
	v_mfma_f32_16x16x32_bf16 v[62:65], v[140:143], v[178:181], v[62:65]
	v_mfma_f32_16x16x32_bf16 v[58:61], v[154:157], v[178:181], v[58:61]
	v_mfma_f32_16x16x32_bf16 v[46:49], v[140:143], v[188:191], v[46:49]
	v_mfma_f32_16x16x32_bf16 v[42:45], v[154:157], v[188:191], v[42:45]
	v_mfma_f32_16x16x32_bf16 v[30:33], v[140:143], v[210:213], v[30:33]
	v_mfma_f32_16x16x32_bf16 v[26:29], v[154:157], v[210:213], v[26:29]
	v_mfma_f32_16x16x32_bf16 v[14:17], v[140:143], v[218:221], v[14:17]
	v_mfma_f32_16x16x32_bf16 v[10:13], v[154:157], v[218:221], v[10:13]
	v_mfma_f32_16x16x32_bf16 v[62:65], v[150:153], v[184:187], v[62:65]
	v_mfma_f32_16x16x32_bf16 v[58:61], v[158:161], v[184:187], v[58:61]
	v_mfma_f32_16x16x32_bf16 v[46:49], v[150:153], v[196:199], v[46:49]
	v_mfma_f32_16x16x32_bf16 v[42:45], v[158:161], v[196:199], v[42:45]
	v_mfma_f32_16x16x32_bf16 v[30:33], v[150:153], v[214:217], v[30:33]
	v_mfma_f32_16x16x32_bf16 v[26:29], v[158:161], v[214:217], v[26:29]
	v_mfma_f32_16x16x32_bf16 v[14:17], v[150:153], v[222:225], v[14:17]
	v_mfma_f32_16x16x32_bf16 v[10:13], v[158:161], v[222:225], v[10:13]
	v_mfma_f32_16x16x32_bf16 v[54:57], v[162:165], v[178:181], v[54:57]
	v_mfma_f32_16x16x32_bf16 v[50:53], v[170:173], v[178:181], v[50:53]
	v_mfma_f32_16x16x32_bf16 v[38:41], v[162:165], v[188:191], v[38:41]
	v_mfma_f32_16x16x32_bf16 v[34:37], v[170:173], v[188:191], v[34:37]
	v_mfma_f32_16x16x32_bf16 v[22:25], v[162:165], v[210:213], v[22:25]
	v_mfma_f32_16x16x32_bf16 v[18:21], v[170:173], v[210:213], v[18:21]
	v_mfma_f32_16x16x32_bf16 v[6:9], v[162:165], v[218:221], v[6:9]
	v_mfma_f32_16x16x32_bf16 v[2:5], v[170:173], v[218:221], v[2:5]
	v_mfma_f32_16x16x32_bf16 v[54:57], v[166:169], v[184:187], v[54:57]
	v_mfma_f32_16x16x32_bf16 v[50:53], v[174:177], v[184:187], v[50:53]
	v_mfma_f32_16x16x32_bf16 v[38:41], v[166:169], v[196:199], v[38:41]
	v_mfma_f32_16x16x32_bf16 v[34:37], v[174:177], v[196:199], v[34:37]
	v_mfma_f32_16x16x32_bf16 v[22:25], v[166:169], v[214:217], v[22:25]
	v_mfma_f32_16x16x32_bf16 v[18:21], v[174:177], v[214:217], v[18:21]
	v_mfma_f32_16x16x32_bf16 v[6:9], v[166:169], v[222:225], v[6:9]
	v_mfma_f32_16x16x32_bf16 v[2:5], v[174:177], v[222:225], v[2:5]
	s_barrier
	s_add_i32 s50, s50, 2
	s_add_u32 s34, s34, 0x100
	s_addc_u32 s35, s35, 0
	s_add_u32 s48, s48, 0x100
	s_addc_u32 s49, s49, 0
	s_cmp_gt_u32 s50, 13
	s_cbranch_scc0 .LBB0_792
	s_setprio 0
	s_and_b64 vcc, exec, s[10:11]
	s_cbranch_vccz .LBB0_795
	s_barrier

.Lsprio_3:
.LBB0_864:
	s_add_u32 s30, s12, 0xfff00080
	s_addc_u32 s31, s13, -1
	s_add_i32 s45, 0, 0x10000
	s_cmp_eq_u32 s35, 60
	s_cselect_b32 s37, s3, s31
	s_cselect_b32 s36, s16, s30
	s_cselect_b32 s31, s24, s28
	s_cselect_b32 s30, s25, s26
	s_add_i32 s59, 0, 0x14000
	v_add_u32_e32 v156, s45, v145
	v_add_u32_e32 v172, s59, v145
	ds_read_b128 v[140:143], v156
	ds_read_b128 v[148:151], v156 offset:1024
	ds_read_b128 v[152:155], v156 offset:2048
	ds_read_b128 v[156:159], v156 offset:3072
	ds_read_b128 v[160:163], v172
	ds_read_b128 v[164:167], v172 offset:1024
	ds_read_b128 v[168:171], v172 offset:2048
	ds_read_b128 v[172:175], v172 offset:3072
	v_lshl_add_u64 v[180:181], s[12:13], 0, v[136:137]
	s_add_i32 m0, s51, 0xc000
	ds_read_b128 v[176:179], v147
	ds_read_b128 v[184:187], v147 offset:1024
	ds_read_b128 v[188:191], v147 offset:2048
	ds_read_b128 v[196:199], v147 offset:3072
	ds_read_b128 v[210:213], v147 offset:4096
	ds_read_b128 v[214:217], v147 offset:5120
	ds_read_b128 v[218:221], v147 offset:6144
	ds_read_b128 v[222:225], v147 offset:7168
	global_load_lds_dwordx4 v[180:181], off
	v_lshl_add_u64 v[180:181], s[12:13], 0, v[138:139]
	s_add_i32 m0, s51, 0xe000
	s_nop 0
	global_load_lds_dwordx4 v[180:181], off
	s_waitcnt vmcnt(8)
	s_waitcnt lgkmcnt(0)
	s_barrier
	v_mfma_f32_16x16x32_bf16 v[126:129], v[140:143], v[176:179], v[126:129]
	v_mfma_f32_16x16x32_bf16 v[122:125], v[152:155], v[176:179], v[122:125]
	v_mfma_f32_16x16x32_bf16 v[110:113], v[140:143], v[188:191], v[110:113]
	v_mfma_f32_16x16x32_bf16 v[106:109], v[152:155], v[188:191], v[106:109]
	v_mfma_f32_16x16x32_bf16 v[94:97], v[140:143], v[210:213], v[94:97]
	v_mfma_f32_16x16x32_bf16 v[90:93], v[152:155], v[210:213], v[90:93]
	v_mfma_f32_16x16x32_bf16 v[78:81], v[140:143], v[218:221], v[78:81]
	v_mfma_f32_16x16x32_bf16 v[74:77], v[152:155], v[218:221], v[74:77]
	v_mfma_f32_16x16x32_bf16 v[126:129], v[148:151], v[184:187], v[126:129]
	v_mfma_f32_16x16x32_bf16 v[122:125], v[156:159], v[184:187], v[122:125]
	v_mfma_f32_16x16x32_bf16 v[110:113], v[148:151], v[196:199], v[110:113]
	v_mfma_f32_16x16x32_bf16 v[106:109], v[156:159], v[196:199], v[106:109]
	v_mfma_f32_16x16x32_bf16 v[94:97], v[148:151], v[214:217], v[94:97]
	v_mfma_f32_16x16x32_bf16 v[90:93], v[156:159], v[214:217], v[90:93]
	v_mfma_f32_16x16x32_bf16 v[78:81], v[148:151], v[222:225], v[78:81]
	v_mfma_f32_16x16x32_bf16 v[74:77], v[156:159], v[222:225], v[74:77]
	v_mfma_f32_16x16x32_bf16 v[118:121], v[160:163], v[176:179], v[118:121]
	v_mfma_f32_16x16x32_bf16 v[114:117], v[168:171], v[176:179], v[114:117]
	v_mfma_f32_16x16x32_bf16 v[102:105], v[160:163], v[188:191], v[102:105]
	v_mfma_f32_16x16x32_bf16 v[98:101], v[168:171], v[188:191], v[98:101]
	v_mfma_f32_16x16x32_bf16 v[86:89], v[160:163], v[210:213], v[86:89]
	v_mfma_f32_16x16x32_bf16 v[82:85], v[168:171], v[210:213], v[82:85]
	v_mfma_f32_16x16x32_bf16 v[70:73], v[160:163], v[218:221], v[70:73]
	v_mfma_f32_16x16x32_bf16 v[66:69], v[168:171], v[218:221], v[66:69]
	v_mfma_f32_16x16x32_bf16 v[118:121], v[164:167], v[184:187], v[118:121]
	v_mfma_f32_16x16x32_bf16 v[114:117], v[172:175], v[184:187], v[114:117]
	v_mfma_f32_16x16x32_bf16 v[102:105], v[164:167], v[196:199], v[102:105]
	v_mfma_f32_16x16x32_bf16 v[98:101], v[172:175], v[196:199], v[98:101]
	v_mfma_f32_16x16x32_bf16 v[86:89], v[164:167], v[214:217], v[86:89]
	v_mfma_f32_16x16x32_bf16 v[82:85], v[172:175], v[214:217], v[82:85]
	v_mfma_f32_16x16x32_bf16 v[70:73], v[164:167], v[222:225], v[70:73]
	v_mfma_f32_16x16x32_bf16 v[66:69], v[172:175], v[222:225], v[66:69]
	s_barrier
	s_add_i32 s45, s45, s50
	v_lshl_add_u64 v[180:181], s[30:31], 0, v[0:1]
	s_mov_b32 m0, s45
	ds_read_b128 v[176:179], v147 offset:16384
	ds_read_b128 v[184:187], v147 offset:17408
	ds_read_b128 v[188:191], v147 offset:18432
	ds_read_b128 v[196:199], v147 offset:19456
	ds_read_b128 v[210:213], v147 offset:20480
	ds_read_b128 v[214:217], v147 offset:21504
	ds_read_b128 v[218:221], v147 offset:22528
	ds_read_b128 v[222:225], v147 offset:23552
	global_load_lds_dwordx4 v[180:181], off
	s_add_i32 m0, s45, 0x2000
	s_add_u32 s60, s30, 0x100000
	v_lshl_add_u64 v[192:193], s[30:31], 0, v[130:131]
	s_addc_u32 s61, s31, 0
	s_add_i32 s45, s59, s50
	global_load_lds_dwordx4 v[192:193], off
	v_lshl_add_u64 v[202:203], s[60:61], 0, v[0:1]
	s_mov_b32 m0, s45
	v_lshl_add_u64 v[226:227], s[36:37], 0, v[132:133]
	global_load_lds_dwordx4 v[202:203], off
	v_lshl_add_u64 v[202:203], s[60:61], 0, v[130:131]
	s_add_i32 m0, s45, 0x2000
	s_nop 0
	global_load_lds_dwordx4 v[202:203], off
	v_lshl_add_u64 v[202:203], s[36:37], 0, v[134:135]
	s_mov_b32 m0, s51
	s_nop 0
	global_load_lds_dwordx4 v[202:203], off
	s_mov_b32 m0, s52
	s_nop 0
	global_load_lds_dwordx4 v[226:227], off
	s_waitcnt vmcnt(8)
	s_waitcnt lgkmcnt(0)
	s_barrier
	v_mfma_f32_16x16x32_bf16 v[62:65], v[140:143], v[176:179], v[62:65]
	v_mfma_f32_16x16x32_bf16 v[58:61], v[152:155], v[176:179], v[58:61]
	v_mfma_f32_16x16x32_bf16 v[46:49], v[140:143], v[188:191], v[46:49]
	v_mfma_f32_16x16x32_bf16 v[42:45], v[152:155], v[188:191], v[42:45]
	v_mfma_f32_16x16x32_bf16 v[30:33], v[140:143], v[210:213], v[30:33]
	v_mfma_f32_16x16x32_bf16 v[26:29], v[152:155], v[210:213], v[26:29]
	v_mfma_f32_16x16x32_bf16 v[14:17], v[140:143], v[218:221], v[14:17]
	v_mfma_f32_16x16x32_bf16 v[10:13], v[152:155], v[218:221], v[10:13]
	v_mfma_f32_16x16x32_bf16 v[62:65], v[148:151], v[184:187], v[62:65]
	v_mfma_f32_16x16x32_bf16 v[58:61], v[156:159], v[184:187], v[58:61]
	v_mfma_f32_16x16x32_bf16 v[46:49], v[148:151], v[196:199], v[46:49]
	v_mfma_f32_16x16x32_bf16 v[42:45], v[156:159], v[196:199], v[42:45]
	v_mfma_f32_16x16x32_bf16 v[30:33], v[148:151], v[214:217], v[30:33]
	v_mfma_f32_16x16x32_bf16 v[26:29], v[156:159], v[214:217], v[26:29]
	v_mfma_f32_16x16x32_bf16 v[14:17], v[148:151], v[222:225], v[14:17]
	v_mfma_f32_16x16x32_bf16 v[10:13], v[156:159], v[222:225], v[10:13]
	v_mfma_f32_16x16x32_bf16 v[54:57], v[160:163], v[176:179], v[54:57]
	v_mfma_f32_16x16x32_bf16 v[50:53], v[168:171], v[176:179], v[50:53]
	v_mfma_f32_16x16x32_bf16 v[38:41], v[160:163], v[188:191], v[38:41]
	v_mfma_f32_16x16x32_bf16 v[34:37], v[168:171], v[188:191], v[34:37]
	v_mfma_f32_16x16x32_bf16 v[22:25], v[160:163], v[210:213], v[22:25]
	v_mfma_f32_16x16x32_bf16 v[18:21], v[168:171], v[210:213], v[18:21]
	v_mfma_f32_16x16x32_bf16 v[6:9], v[160:163], v[218:221], v[6:9]
	v_mfma_f32_16x16x32_bf16 v[2:5], v[168:171], v[218:221], v[2:5]
	v_mfma_f32_16x16x32_bf16 v[54:57], v[164:167], v[184:187], v[54:57]
	v_mfma_f32_16x16x32_bf16 v[50:53], v[172:175], v[184:187], v[50:53]
	v_mfma_f32_16x16x32_bf16 v[38:41], v[164:167], v[196:199], v[38:41]
	v_mfma_f32_16x16x32_bf16 v[34:37], v[172:175], v[196:199], v[34:37]
	v_mfma_f32_16x16x32_bf16 v[22:25], v[164:167], v[214:217], v[22:25]
	v_mfma_f32_16x16x32_bf16 v[18:21], v[172:175], v[214:217], v[18:21]
	v_mfma_f32_16x16x32_bf16 v[6:9], v[164:167], v[222:225], v[6:9]
	v_mfma_f32_16x16x32_bf16 v[2:5], v[172:175], v[222:225], v[2:5]
	s_barrier
	s_add_i32 s45, 0, 0x18000
	s_add_i32 s59, 0, 0x1c000
	v_add_u32_e32 v156, s45, v145
	v_add_u32_e32 v172, s59, v145
	ds_read_b128 v[140:143], v156
	ds_read_b128 v[148:151], v156 offset:1024
	ds_read_b128 v[152:155], v156 offset:2048
	ds_read_b128 v[156:159], v156 offset:3072
	ds_read_b128 v[160:163], v172
	ds_read_b128 v[164:167], v172 offset:1024
	ds_read_b128 v[168:171], v172 offset:2048
	ds_read_b128 v[172:175], v172 offset:3072
	s_add_u32 s36, s36, 0x100000
	s_addc_u32 s37, s37, 0
	s_mov_b32 m0, s53
	v_lshl_add_u64 v[228:229], s[36:37], 0, v[134:135]
	ds_read_b128 v[176:179], v147 offset:32768
	ds_read_b128 v[184:187], v147 offset:33792
	ds_read_b128 v[188:191], v147 offset:34816
	ds_read_b128 v[196:199], v147 offset:35840
	ds_read_b128 v[210:213], v147 offset:36864
	ds_read_b128 v[214:217], v147 offset:37888
	ds_read_b128 v[218:221], v147 offset:38912
	ds_read_b128 v[222:225], v147 offset:39936
	global_load_lds_dwordx4 v[228:229], off
	v_lshl_add_u64 v[228:229], s[36:37], 0, v[132:133]
	s_mov_b32 m0, s54
	s_nop 0
	global_load_lds_dwordx4 v[228:229], off
	s_waitcnt vmcnt(8)
	s_waitcnt lgkmcnt(0)
	s_barrier
	v_mfma_f32_16x16x32_bf16 v[126:129], v[140:143], v[176:179], v[126:129]
	v_mfma_f32_16x16x32_bf16 v[122:125], v[152:155], v[176:179], v[122:125]
	v_mfma_f32_16x16x32_bf16 v[110:113], v[140:143], v[188:191], v[110:113]
	v_mfma_f32_16x16x32_bf16 v[106:109], v[152:155], v[188:191], v[106:109]
	v_mfma_f32_16x16x32_bf16 v[94:97], v[140:143], v[210:213], v[94:97]
	v_mfma_f32_16x16x32_bf16 v[90:93], v[152:155], v[210:213], v[90:93]
	v_mfma_f32_16x16x32_bf16 v[78:81], v[140:143], v[218:221], v[78:81]
	v_mfma_f32_16x16x32_bf16 v[74:77], v[152:155], v[218:221], v[74:77]
	v_mfma_f32_16x16x32_bf16 v[126:129], v[148:151], v[184:187], v[126:129]
	v_mfma_f32_16x16x32_bf16 v[122:125], v[156:159], v[184:187], v[122:125]
	v_mfma_f32_16x16x32_bf16 v[110:113], v[148:151], v[196:199], v[110:113]
	v_mfma_f32_16x16x32_bf16 v[106:109], v[156:159], v[196:199], v[106:109]
	v_mfma_f32_16x16x32_bf16 v[94:97], v[148:151], v[214:217], v[94:97]
	v_mfma_f32_16x16x32_bf16 v[90:93], v[156:159], v[214:217], v[90:93]
	v_mfma_f32_16x16x32_bf16 v[78:81], v[148:151], v[222:225], v[78:81]
	v_mfma_f32_16x16x32_bf16 v[74:77], v[156:159], v[222:225], v[74:77]
	v_mfma_f32_16x16x32_bf16 v[118:121], v[160:163], v[176:179], v[118:121]
	v_mfma_f32_16x16x32_bf16 v[114:117], v[168:171], v[176:179], v[114:117]
	v_mfma_f32_16x16x32_bf16 v[102:105], v[160:163], v[188:191], v[102:105]
	v_mfma_f32_16x16x32_bf16 v[98:101], v[168:171], v[188:191], v[98:101]
	v_mfma_f32_16x16x32_bf16 v[86:89], v[160:163], v[210:213], v[86:89]
	v_mfma_f32_16x16x32_bf16 v[82:85], v[168:171], v[210:213], v[82:85]
	v_mfma_f32_16x16x32_bf16 v[70:73], v[160:163], v[218:221], v[70:73]
	v_mfma_f32_16x16x32_bf16 v[66:69], v[168:171], v[218:221], v[66:69]
	v_mfma_f32_16x16x32_bf16 v[118:121], v[164:167], v[184:187], v[118:121]
	v_mfma_f32_16x16x32_bf16 v[114:117], v[172:175], v[184:187], v[114:117]
	v_mfma_f32_16x16x32_bf16 v[102:105], v[164:167], v[196:199], v[102:105]
	v_mfma_f32_16x16x32_bf16 v[98:101], v[172:175], v[196:199], v[98:101]
	v_mfma_f32_16x16x32_bf16 v[86:89], v[164:167], v[214:217], v[86:89]
	v_mfma_f32_16x16x32_bf16 v[82:85], v[172:175], v[214:217], v[82:85]
	v_mfma_f32_16x16x32_bf16 v[70:73], v[164:167], v[222:225], v[70:73]
	v_mfma_f32_16x16x32_bf16 v[66:69], v[172:175], v[222:225], v[66:69]
	s_barrier
	s_add_i32 s36, s45, s50
	v_lshl_add_u64 v[180:181], v[180:181], 0, s[22:23]
	s_mov_b32 m0, s36
	ds_read_b128 v[176:179], v147 offset:49152
	ds_read_b128 v[184:187], v147 offset:50176
	ds_read_b128 v[188:191], v147 offset:51200
	ds_read_b128 v[196:199], v147 offset:52224
	ds_read_b128 v[210:213], v147 offset:53248
	ds_read_b128 v[214:217], v147 offset:54272
	ds_read_b128 v[218:221], v147 offset:55296
	ds_read_b128 v[222:225], v147 offset:56320
	global_load_lds_dwordx4 v[180:181], off
	s_add_i32 m0, s36, 0x2000
	s_add_u32 s30, s30, 0x100080
	v_lshl_add_u64 v[180:181], v[192:193], 0, s[22:23]
	s_addc_u32 s31, s31, 0
	s_add_i32 s36, s59, s50
	global_load_lds_dwordx4 v[180:181], off
	v_lshl_add_u64 v[180:181], s[30:31], 0, v[0:1]
	s_mov_b32 m0, s36
	s_nop 0
	global_load_lds_dwordx4 v[180:181], off
	v_lshl_add_u64 v[180:181], s[30:31], 0, v[130:131]
	s_add_i32 m0, s36, 0x2000
	s_nop 0
	global_load_lds_dwordx4 v[180:181], off
	v_lshl_add_u64 v[180:181], v[202:203], 0, s[22:23]
	s_mov_b32 m0, s56
	s_nop 0
	global_load_lds_dwordx4 v[180:181], off
	v_lshl_add_u64 v[180:181], v[226:227], 0, s[22:23]
	s_mov_b32 m0, s57
	s_nop 0
	global_load_lds_dwordx4 v[180:181], off
	s_waitcnt vmcnt(8)
	s_waitcnt lgkmcnt(0)
	s_barrier
	v_mfma_f32_16x16x32_bf16 v[62:65], v[140:143], v[176:179], v[62:65]
	v_mfma_f32_16x16x32_bf16 v[58:61], v[152:155], v[176:179], v[58:61]
	v_mfma_f32_16x16x32_bf16 v[46:49], v[140:143], v[188:191], v[46:49]
	v_mfma_f32_16x16x32_bf16 v[42:45], v[152:155], v[188:191], v[42:45]
	v_mfma_f32_16x16x32_bf16 v[30:33], v[140:143], v[210:213], v[30:33]
	v_mfma_f32_16x16x32_bf16 v[26:29], v[152:155], v[210:213], v[26:29]
	v_mfma_f32_16x16x32_bf16 v[14:17], v[140:143], v[218:221], v[14:17]
	v_mfma_f32_16x16x32_bf16 v[10:13], v[152:155], v[218:221], v[10:13]
	v_mfma_f32_16x16x32_bf16 v[62:65], v[148:151], v[184:187], v[62:65]
	v_mfma_f32_16x16x32_bf16 v[58:61], v[156:159], v[184:187], v[58:61]
	v_mfma_f32_16x16x32_bf16 v[46:49], v[148:151], v[196:199], v[46:49]
	v_mfma_f32_16x16x32_bf16 v[42:45], v[156:159], v[196:199], v[42:45]
	v_mfma_f32_16x16x32_bf16 v[30:33], v[148:151], v[214:217], v[30:33]
	v_mfma_f32_16x16x32_bf16 v[26:29], v[156:159], v[214:217], v[26:29]
	v_mfma_f32_16x16x32_bf16 v[14:17], v[148:151], v[222:225], v[14:17]
	v_mfma_f32_16x16x32_bf16 v[10:13], v[156:159], v[222:225], v[10:13]
	v_mfma_f32_16x16x32_bf16 v[54:57], v[160:163], v[176:179], v[54:57]
	v_mfma_f32_16x16x32_bf16 v[50:53], v[168:171], v[176:179], v[50:53]
	v_mfma_f32_16x16x32_bf16 v[38:41], v[160:163], v[188:191], v[38:41]
	v_mfma_f32_16x16x32_bf16 v[34:37], v[168:171], v[188:191], v[34:37]
	v_mfma_f32_16x16x32_bf16 v[22:25], v[160:163], v[210:213], v[22:25]
	v_mfma_f32_16x16x32_bf16 v[18:21], v[168:171], v[210:213], v[18:21]
	v_mfma_f32_16x16x32_bf16 v[6:9], v[160:163], v[218:221], v[6:9]
	v_mfma_f32_16x16x32_bf16 v[2:5], v[168:171], v[218:221], v[2:5]
	v_mfma_f32_16x16x32_bf16 v[54:57], v[164:167], v[184:187], v[54:57]
	v_mfma_f32_16x16x32_bf16 v[50:53], v[172:175], v[184:187], v[50:53]
	v_mfma_f32_16x16x32_bf16 v[38:41], v[164:167], v[196:199], v[38:41]
	v_mfma_f32_16x16x32_bf16 v[34:37], v[172:175], v[196:199], v[34:37]
	v_mfma_f32_16x16x32_bf16 v[22:25], v[164:167], v[214:217], v[22:25]
	v_mfma_f32_16x16x32_bf16 v[18:21], v[172:175], v[214:217], v[18:21]
	v_mfma_f32_16x16x32_bf16 v[6:9], v[164:167], v[222:225], v[6:9]
	v_mfma_f32_16x16x32_bf16 v[2:5], v[172:175], v[222:225], v[2:5]
	s_barrier
	s_add_i32 s35, s35, 2
	s_add_u32 s12, s12, 0x100
	s_addc_u32 s13, s13, 0
	s_add_u32 s26, s26, 0x100
	s_addc_u32 s28, s28, 0
	s_cmp_gt_u32 s35, 61
	s_cbranch_scc0 .LBB0_864
	s_setprio 0
	s_and_b64 vcc, exec, s[20:21]
	s_cbranch_vccz .LBB0_867
	s_barrier

.Lsprio_4:
.LBB0_957:
	s_add_i32 s52, s40, 2
	s_add_u32 s53, s36, 0x80
	s_addc_u32 s41, s37, 0
	s_add_i32 s56, 0, 0x10000
	s_cmp_eq_u32 s44, s40
	s_cselect_b32 s41, s7, s41
	s_cselect_b32 s40, s6, s53
	s_cselect_b32 s55, s35, s51
	s_cselect_b32 s54, s34, s50
	s_add_i32 s53, 0, 0x14000
	v_add_u32_e32 v154, s56, v140
	v_add_u32_e32 v170, s53, v140
	ds_read_b128 v[142:145], v154
	ds_read_b128 v[146:149], v154 offset:1024
	ds_read_b128 v[150:153], v154 offset:2048
	ds_read_b128 v[154:157], v154 offset:3072
	ds_read_b128 v[158:161], v170
	ds_read_b128 v[162:165], v170 offset:1024
	ds_read_b128 v[166:169], v170 offset:2048
	ds_read_b128 v[170:173], v170 offset:3072
	v_lshl_add_u64 v[192:193], s[36:37], 0, v[136:137]
	s_add_i32 m0, s18, 0xc000
	ds_read_b128 v[174:177], v141
	ds_read_b128 v[178:181], v141 offset:1024
	ds_read_b128 v[184:187], v141 offset:2048
	ds_read_b128 v[188:191], v141 offset:3072
	ds_read_b128 v[196:199], v141 offset:4096
	ds_read_b128 v[210:213], v141 offset:5120
	ds_read_b128 v[214:217], v141 offset:6144
	ds_read_b128 v[218:221], v141 offset:7168
	global_load_lds_dwordx4 v[192:193], off
	v_lshl_add_u64 v[192:193], s[36:37], 0, v[138:139]
	s_add_i32 m0, s18, 0xe000
	s_nop 0
	global_load_lds_dwordx4 v[192:193], off
	s_waitcnt vmcnt(8)
	s_waitcnt lgkmcnt(0)
	s_barrier
	v_mfma_f32_16x16x32_bf16 v[122:125], v[142:145], v[174:177], v[122:125]
	v_mfma_f32_16x16x32_bf16 v[126:129], v[150:153], v[174:177], v[126:129]
	v_mfma_f32_16x16x32_bf16 v[110:113], v[142:145], v[184:187], v[110:113]
	v_mfma_f32_16x16x32_bf16 v[106:109], v[150:153], v[184:187], v[106:109]
	v_mfma_f32_16x16x32_bf16 v[94:97], v[142:145], v[196:199], v[94:97]
	v_mfma_f32_16x16x32_bf16 v[90:93], v[150:153], v[196:199], v[90:93]
	v_mfma_f32_16x16x32_bf16 v[78:81], v[142:145], v[214:217], v[78:81]
	v_mfma_f32_16x16x32_bf16 v[74:77], v[150:153], v[214:217], v[74:77]
	v_mfma_f32_16x16x32_bf16 v[122:125], v[146:149], v[178:181], v[122:125]
	v_mfma_f32_16x16x32_bf16 v[126:129], v[154:157], v[178:181], v[126:129]
	v_mfma_f32_16x16x32_bf16 v[110:113], v[146:149], v[188:191], v[110:113]
	v_mfma_f32_16x16x32_bf16 v[106:109], v[154:157], v[188:191], v[106:109]
	v_mfma_f32_16x16x32_bf16 v[94:97], v[146:149], v[210:213], v[94:97]
	v_mfma_f32_16x16x32_bf16 v[90:93], v[154:157], v[210:213], v[90:93]
	v_mfma_f32_16x16x32_bf16 v[78:81], v[146:149], v[218:221], v[78:81]
	v_mfma_f32_16x16x32_bf16 v[74:77], v[154:157], v[218:221], v[74:77]
	v_mfma_f32_16x16x32_bf16 v[118:121], v[158:161], v[174:177], v[118:121]
	v_mfma_f32_16x16x32_bf16 v[114:117], v[166:169], v[174:177], v[114:117]
	v_mfma_f32_16x16x32_bf16 v[102:105], v[158:161], v[184:187], v[102:105]
	v_mfma_f32_16x16x32_bf16 v[98:101], v[166:169], v[184:187], v[98:101]
	v_mfma_f32_16x16x32_bf16 v[86:89], v[158:161], v[196:199], v[86:89]
	v_mfma_f32_16x16x32_bf16 v[82:85], v[166:169], v[196:199], v[82:85]
	v_mfma_f32_16x16x32_bf16 v[70:73], v[158:161], v[214:217], v[70:73]
	v_mfma_f32_16x16x32_bf16 v[66:69], v[166:169], v[214:217], v[66:69]
	v_mfma_f32_16x16x32_bf16 v[118:121], v[162:165], v[178:181], v[118:121]
	v_mfma_f32_16x16x32_bf16 v[114:117], v[170:173], v[178:181], v[114:117]
	v_mfma_f32_16x16x32_bf16 v[102:105], v[162:165], v[188:191], v[102:105]
	v_mfma_f32_16x16x32_bf16 v[98:101], v[170:173], v[188:191], v[98:101]
	v_mfma_f32_16x16x32_bf16 v[86:89], v[162:165], v[210:213], v[86:89]
	v_mfma_f32_16x16x32_bf16 v[82:85], v[170:173], v[210:213], v[82:85]
	v_mfma_f32_16x16x32_bf16 v[70:73], v[162:165], v[218:221], v[70:73]
	v_mfma_f32_16x16x32_bf16 v[66:69], v[170:173], v[218:221], v[66:69]
	s_barrier
	s_add_i32 s56, s56, s17
	v_lshl_add_u64 v[192:193], s[54:55], 0, v[0:1]
	s_mov_b32 m0, s56
	ds_read_b128 v[174:177], v141 offset:16384
	ds_read_b128 v[178:181], v141 offset:17408
	ds_read_b128 v[184:187], v141 offset:18432
	ds_read_b128 v[188:191], v141 offset:19456
	ds_read_b128 v[196:199], v141 offset:20480
	ds_read_b128 v[210:213], v141 offset:21504
	ds_read_b128 v[214:217], v141 offset:22528
	ds_read_b128 v[218:221], v141 offset:23552
	global_load_lds_dwordx4 v[192:193], off
	s_add_i32 m0, s56, 0x2000
	v_lshl_add_u64 v[202:203], s[54:55], 0, v[130:131]
	s_add_u32 s54, s54, s10
	s_addc_u32 s55, s55, s11
	s_add_i32 s53, s53, s17
	global_load_lds_dwordx4 v[202:203], off
	v_lshl_add_u64 v[222:223], s[54:55], 0, v[0:1]
	s_mov_b32 m0, s53
	v_lshl_add_u64 v[224:225], s[54:55], 0, v[130:131]
	global_load_lds_dwordx4 v[222:223], off
	s_add_i32 m0, s53, 0x2000
	v_lshl_add_u64 v[226:227], s[40:41], 0, v[134:135]
	global_load_lds_dwordx4 v[224:225], off
	s_mov_b32 m0, s18
	v_lshl_add_u64 v[228:229], s[40:41], 0, v[132:133]
	global_load_lds_dwordx4 v[226:227], off
	s_mov_b32 m0, s19
	s_nop 0
	global_load_lds_dwordx4 v[228:229], off
	s_waitcnt vmcnt(8)
	s_waitcnt lgkmcnt(0)
	s_barrier
	v_mfma_f32_16x16x32_bf16 v[62:65], v[142:145], v[174:177], v[62:65]
	v_mfma_f32_16x16x32_bf16 v[58:61], v[150:153], v[174:177], v[58:61]
	v_mfma_f32_16x16x32_bf16 v[46:49], v[142:145], v[184:187], v[46:49]
	v_mfma_f32_16x16x32_bf16 v[42:45], v[150:153], v[184:187], v[42:45]
	v_mfma_f32_16x16x32_bf16 v[30:33], v[142:145], v[196:199], v[30:33]
	v_mfma_f32_16x16x32_bf16 v[26:29], v[150:153], v[196:199], v[26:29]
	v_mfma_f32_16x16x32_bf16 v[14:17], v[142:145], v[214:217], v[14:17]
	v_mfma_f32_16x16x32_bf16 v[10:13], v[150:153], v[214:217], v[10:13]
	v_mfma_f32_16x16x32_bf16 v[62:65], v[146:149], v[178:181], v[62:65]
	v_mfma_f32_16x16x32_bf16 v[58:61], v[154:157], v[178:181], v[58:61]
	v_mfma_f32_16x16x32_bf16 v[46:49], v[146:149], v[188:191], v[46:49]
	v_mfma_f32_16x16x32_bf16 v[42:45], v[154:157], v[188:191], v[42:45]
	v_mfma_f32_16x16x32_bf16 v[30:33], v[146:149], v[210:213], v[30:33]
	v_mfma_f32_16x16x32_bf16 v[26:29], v[154:157], v[210:213], v[26:29]
	v_mfma_f32_16x16x32_bf16 v[14:17], v[146:149], v[218:221], v[14:17]
	v_mfma_f32_16x16x32_bf16 v[10:13], v[154:157], v[218:221], v[10:13]
	v_mfma_f32_16x16x32_bf16 v[54:57], v[158:161], v[174:177], v[54:57]
	v_mfma_f32_16x16x32_bf16 v[50:53], v[166:169], v[174:177], v[50:53]
	v_mfma_f32_16x16x32_bf16 v[38:41], v[158:161], v[184:187], v[38:41]
	v_mfma_f32_16x16x32_bf16 v[34:37], v[166:169], v[184:187], v[34:37]
	v_mfma_f32_16x16x32_bf16 v[22:25], v[158:161], v[196:199], v[22:25]
	v_mfma_f32_16x16x32_bf16 v[18:21], v[166:169], v[196:199], v[18:21]
	v_mfma_f32_16x16x32_bf16 v[6:9], v[158:161], v[214:217], v[6:9]
	v_mfma_f32_16x16x32_bf16 v[2:5], v[166:169], v[214:217], v[2:5]
	v_mfma_f32_16x16x32_bf16 v[54:57], v[162:165], v[178:181], v[54:57]
	v_mfma_f32_16x16x32_bf16 v[50:53], v[170:173], v[178:181], v[50:53]
	v_mfma_f32_16x16x32_bf16 v[38:41], v[162:165], v[188:191], v[38:41]
	v_mfma_f32_16x16x32_bf16 v[34:37], v[170:173], v[188:191], v[34:37]
	v_mfma_f32_16x16x32_bf16 v[22:25], v[162:165], v[210:213], v[22:25]
	v_mfma_f32_16x16x32_bf16 v[18:21], v[170:173], v[210:213], v[18:21]
	v_mfma_f32_16x16x32_bf16 v[6:9], v[162:165], v[218:221], v[6:9]
	v_mfma_f32_16x16x32_bf16 v[2:5], v[170:173], v[218:221], v[2:5]
	s_barrier
	s_add_i32 s53, 0, 0x18000
	s_add_i32 s54, 0, 0x1c000
	v_add_u32_e32 v154, s53, v140
	v_add_u32_e32 v170, s54, v140
	ds_read_b128 v[142:145], v154
	ds_read_b128 v[146:149], v154 offset:1024
	ds_read_b128 v[150:153], v154 offset:2048
	ds_read_b128 v[154:157], v154 offset:3072
	ds_read_b128 v[158:161], v170
	ds_read_b128 v[162:165], v170 offset:1024
	ds_read_b128 v[166:169], v170 offset:2048
	ds_read_b128 v[170:173], v170 offset:3072
	s_add_u32 s40, s40, s10
	s_addc_u32 s41, s41, s11
	s_mov_b32 m0, s24
	v_lshl_add_u64 v[230:231], s[40:41], 0, v[134:135]
	ds_read_b128 v[174:177], v141 offset:32768
	ds_read_b128 v[178:181], v141 offset:33792
	ds_read_b128 v[184:187], v141 offset:34816
	ds_read_b128 v[188:191], v141 offset:35840
	ds_read_b128 v[196:199], v141 offset:36864
	ds_read_b128 v[210:213], v141 offset:37888
	ds_read_b128 v[214:217], v141 offset:38912
	ds_read_b128 v[218:221], v141 offset:39936
	global_load_lds_dwordx4 v[230:231], off
	v_lshl_add_u64 v[230:231], s[40:41], 0, v[132:133]
	s_mov_b32 m0, s25
	s_nop 0
	global_load_lds_dwordx4 v[230:231], off
	s_waitcnt vmcnt(8)
	s_waitcnt lgkmcnt(0)
	s_barrier
	v_mfma_f32_16x16x32_bf16 v[122:125], v[142:145], v[174:177], v[122:125]
	v_mfma_f32_16x16x32_bf16 v[126:129], v[150:153], v[174:177], v[126:129]
	v_mfma_f32_16x16x32_bf16 v[110:113], v[142:145], v[184:187], v[110:113]
	v_mfma_f32_16x16x32_bf16 v[106:109], v[150:153], v[184:187], v[106:109]
	v_mfma_f32_16x16x32_bf16 v[94:97], v[142:145], v[196:199], v[94:97]
	v_mfma_f32_16x16x32_bf16 v[90:93], v[150:153], v[196:199], v[90:93]
	v_mfma_f32_16x16x32_bf16 v[78:81], v[142:145], v[214:217], v[78:81]
	v_mfma_f32_16x16x32_bf16 v[74:77], v[150:153], v[214:217], v[74:77]
	v_mfma_f32_16x16x32_bf16 v[122:125], v[146:149], v[178:181], v[122:125]
	v_mfma_f32_16x16x32_bf16 v[126:129], v[154:157], v[178:181], v[126:129]
	v_mfma_f32_16x16x32_bf16 v[110:113], v[146:149], v[188:191], v[110:113]
	v_mfma_f32_16x16x32_bf16 v[106:109], v[154:157], v[188:191], v[106:109]
	v_mfma_f32_16x16x32_bf16 v[94:97], v[146:149], v[210:213], v[94:97]
	v_mfma_f32_16x16x32_bf16 v[90:93], v[154:157], v[210:213], v[90:93]
	v_mfma_f32_16x16x32_bf16 v[78:81], v[146:149], v[218:221], v[78:81]
	v_mfma_f32_16x16x32_bf16 v[74:77], v[154:157], v[218:221], v[74:77]
	v_mfma_f32_16x16x32_bf16 v[118:121], v[158:161], v[174:177], v[118:121]
	v_mfma_f32_16x16x32_bf16 v[114:117], v[166:169], v[174:177], v[114:117]
	v_mfma_f32_16x16x32_bf16 v[102:105], v[158:161], v[184:187], v[102:105]
	v_mfma_f32_16x16x32_bf16 v[98:101], v[166:169], v[184:187], v[98:101]
	v_mfma_f32_16x16x32_bf16 v[86:89], v[158:161], v[196:199], v[86:89]
	v_mfma_f32_16x16x32_bf16 v[82:85], v[166:169], v[196:199], v[82:85]
	v_mfma_f32_16x16x32_bf16 v[70:73], v[158:161], v[214:217], v[70:73]
	v_mfma_f32_16x16x32_bf16 v[66:69], v[166:169], v[214:217], v[66:69]
	v_mfma_f32_16x16x32_bf16 v[118:121], v[162:165], v[178:181], v[118:121]
	v_mfma_f32_16x16x32_bf16 v[114:117], v[170:173], v[178:181], v[114:117]
	v_mfma_f32_16x16x32_bf16 v[102:105], v[162:165], v[188:191], v[102:105]
	v_mfma_f32_16x16x32_bf16 v[98:101], v[170:173], v[188:191], v[98:101]
	v_mfma_f32_16x16x32_bf16 v[86:89], v[162:165], v[210:213], v[86:89]
	v_mfma_f32_16x16x32_bf16 v[82:85], v[170:173], v[210:213], v[82:85]
	v_mfma_f32_16x16x32_bf16 v[70:73], v[162:165], v[218:221], v[70:73]
	v_mfma_f32_16x16x32_bf16 v[66:69], v[170:173], v[218:221], v[66:69]
	s_barrier
	s_add_i32 s40, s53, s17
	v_lshl_add_u64 v[192:193], v[192:193], 0, s[22:23]
	s_mov_b32 m0, s40
	ds_read_b128 v[174:177], v141 offset:49152
	ds_read_b128 v[178:181], v141 offset:50176
	ds_read_b128 v[184:187], v141 offset:51200
	ds_read_b128 v[188:191], v141 offset:52224
	ds_read_b128 v[196:199], v141 offset:53248
	ds_read_b128 v[210:213], v141 offset:54272
	ds_read_b128 v[214:217], v141 offset:55296
	ds_read_b128 v[218:221], v141 offset:56320
	global_load_lds_dwordx4 v[192:193], off
	v_lshl_add_u64 v[192:193], v[202:203], 0, s[22:23]
	s_add_i32 m0, s40, 0x2000
	s_add_i32 s40, s54, s17
	global_load_lds_dwordx4 v[192:193], off
	v_lshl_add_u64 v[192:193], v[222:223], 0, s[22:23]
	s_mov_b32 m0, s40
	s_nop 0
	global_load_lds_dwordx4 v[192:193], off
	v_lshl_add_u64 v[192:193], v[224:225], 0, s[22:23]
	s_add_i32 m0, s40, 0x2000
	s_nop 0
	global_load_lds_dwordx4 v[192:193], off
	v_lshl_add_u64 v[192:193], v[226:227], 0, s[22:23]
	s_mov_b32 m0, s42
	s_nop 0
	global_load_lds_dwordx4 v[192:193], off
	v_lshl_add_u64 v[192:193], v[228:229], 0, s[22:23]
	s_mov_b32 m0, s43
	s_nop 0
	global_load_lds_dwordx4 v[192:193], off
	s_waitcnt vmcnt(8)
	s_waitcnt lgkmcnt(0)
	s_barrier
	v_mfma_f32_16x16x32_bf16 v[62:65], v[142:145], v[174:177], v[62:65]
	v_mfma_f32_16x16x32_bf16 v[58:61], v[150:153], v[174:177], v[58:61]
	v_mfma_f32_16x16x32_bf16 v[46:49], v[142:145], v[184:187], v[46:49]
	v_mfma_f32_16x16x32_bf16 v[42:45], v[150:153], v[184:187], v[42:45]
	v_mfma_f32_16x16x32_bf16 v[30:33], v[142:145], v[196:199], v[30:33]
	v_mfma_f32_16x16x32_bf16 v[26:29], v[150:153], v[196:199], v[26:29]
	v_mfma_f32_16x16x32_bf16 v[14:17], v[142:145], v[214:217], v[14:17]
	v_mfma_f32_16x16x32_bf16 v[10:13], v[150:153], v[214:217], v[10:13]
	v_mfma_f32_16x16x32_bf16 v[62:65], v[146:149], v[178:181], v[62:65]
	v_mfma_f32_16x16x32_bf16 v[58:61], v[154:157], v[178:181], v[58:61]
	v_mfma_f32_16x16x32_bf16 v[46:49], v[146:149], v[188:191], v[46:49]
	v_mfma_f32_16x16x32_bf16 v[42:45], v[154:157], v[188:191], v[42:45]
	v_mfma_f32_16x16x32_bf16 v[30:33], v[146:149], v[210:213], v[30:33]
	v_mfma_f32_16x16x32_bf16 v[26:29], v[154:157], v[210:213], v[26:29]
	v_mfma_f32_16x16x32_bf16 v[14:17], v[146:149], v[218:221], v[14:17]
	v_mfma_f32_16x16x32_bf16 v[10:13], v[154:157], v[218:221], v[10:13]
	v_mfma_f32_16x16x32_bf16 v[54:57], v[158:161], v[174:177], v[54:57]
	v_mfma_f32_16x16x32_bf16 v[50:53], v[166:169], v[174:177], v[50:53]
	v_mfma_f32_16x16x32_bf16 v[38:41], v[158:161], v[184:187], v[38:41]
	v_mfma_f32_16x16x32_bf16 v[34:37], v[166:169], v[184:187], v[34:37]
	v_mfma_f32_16x16x32_bf16 v[22:25], v[158:161], v[196:199], v[22:25]
	v_mfma_f32_16x16x32_bf16 v[18:21], v[166:169], v[196:199], v[18:21]
	v_mfma_f32_16x16x32_bf16 v[6:9], v[158:161], v[214:217], v[6:9]
	v_mfma_f32_16x16x32_bf16 v[2:5], v[166:169], v[214:217], v[2:5]
	v_mfma_f32_16x16x32_bf16 v[54:57], v[162:165], v[178:181], v[54:57]
	v_mfma_f32_16x16x32_bf16 v[50:53], v[170:173], v[178:181], v[50:53]
	v_mfma_f32_16x16x32_bf16 v[38:41], v[162:165], v[188:191], v[38:41]
	v_mfma_f32_16x16x32_bf16 v[34:37], v[170:173], v[188:191], v[34:37]
	v_mfma_f32_16x16x32_bf16 v[22:25], v[162:165], v[210:213], v[22:25]
	v_mfma_f32_16x16x32_bf16 v[18:21], v[170:173], v[210:213], v[18:21]
	v_mfma_f32_16x16x32_bf16 v[6:9], v[162:165], v[218:221], v[6:9]
	v_mfma_f32_16x16x32_bf16 v[2:5], v[170:173], v[218:221], v[2:5]
	s_barrier
	s_add_u32 s36, s36, 0x100
	s_addc_u32 s37, s37, 0
	s_add_u32 s50, s50, 0x100
	s_addc_u32 s51, s51, 0
	s_cmp_ge_i32 s52, s29
	s_mov_b32 s40, s52
	s_cbranch_scc0 .LBB0_957
	s_setprio 0

.Lsprio_5:
.LBB0_986:
	s_add_u32 s25, s12, 0xfffc0080
	s_addc_u32 s26, s13, -1
	s_add_i32 s28, 0, 0x10000
	s_cmp_eq_u32 s24, 12
	s_cselect_b32 s37, s3, s26
	s_cselect_b32 s36, s16, s25
	v_add_u32_e32 v144, s28, v147
	s_cselect_b32 s31, s15, s21
	s_cselect_b32 s30, s18, s19
	s_add_i32 s25, 0, 0x14000
	ds_read_b128 v[140:143], v144
	ds_read_b128 v[152:155], v144 offset:1024
	ds_read_b128 v[156:159], v144 offset:2048
	ds_read_b128 v[160:163], v144 offset:3072
	v_add_u32_e32 v144, s25, v147
	ds_read_b128 v[164:167], v144
	ds_read_b128 v[168:171], v144 offset:1024
	ds_read_b128 v[172:175], v144 offset:2048
	ds_read_b128 v[176:179], v144 offset:3072
	v_lshl_add_u64 v[144:145], s[12:13], 0, v[136:137]
	s_add_i32 m0, s47, 0xc000
	ds_read_b128 v[184:187], v150
	ds_read_b128 v[188:191], v150 offset:1024
	ds_read_b128 v[196:199], v150 offset:2048
	ds_read_b128 v[210:213], v150 offset:3072
	ds_read_b128 v[214:217], v150 offset:4096
	ds_read_b128 v[218:221], v150 offset:5120
	ds_read_b128 v[222:225], v150 offset:6144
	ds_read_b128 v[226:229], v150 offset:7168
	global_load_lds_dwordx4 v[144:145], off
	v_lshl_add_u64 v[144:145], s[12:13], 0, v[138:139]
	s_add_i32 m0, s47, 0xe000
	s_nop 0
	global_load_lds_dwordx4 v[144:145], off
	s_waitcnt vmcnt(8)
	s_waitcnt lgkmcnt(0)
	s_barrier
	v_mfma_f32_16x16x32_bf16 v[126:129], v[140:143], v[184:187], v[126:129]
	v_mfma_f32_16x16x32_bf16 v[122:125], v[156:159], v[184:187], v[122:125]
	v_mfma_f32_16x16x32_bf16 v[110:113], v[140:143], v[196:199], v[110:113]
	v_mfma_f32_16x16x32_bf16 v[106:109], v[156:159], v[196:199], v[106:109]
	v_mfma_f32_16x16x32_bf16 v[94:97], v[140:143], v[214:217], v[94:97]
	v_mfma_f32_16x16x32_bf16 v[90:93], v[156:159], v[214:217], v[90:93]
	v_mfma_f32_16x16x32_bf16 v[78:81], v[140:143], v[222:225], v[78:81]
	v_mfma_f32_16x16x32_bf16 v[74:77], v[156:159], v[222:225], v[74:77]
	v_mfma_f32_16x16x32_bf16 v[126:129], v[152:155], v[188:191], v[126:129]
	v_mfma_f32_16x16x32_bf16 v[122:125], v[160:163], v[188:191], v[122:125]
	v_mfma_f32_16x16x32_bf16 v[110:113], v[152:155], v[210:213], v[110:113]
	v_mfma_f32_16x16x32_bf16 v[106:109], v[160:163], v[210:213], v[106:109]
	v_mfma_f32_16x16x32_bf16 v[94:97], v[152:155], v[218:221], v[94:97]
	v_mfma_f32_16x16x32_bf16 v[90:93], v[160:163], v[218:221], v[90:93]
	v_mfma_f32_16x16x32_bf16 v[78:81], v[152:155], v[226:229], v[78:81]
	v_mfma_f32_16x16x32_bf16 v[74:77], v[160:163], v[226:229], v[74:77]
	v_mfma_f32_16x16x32_bf16 v[118:121], v[164:167], v[184:187], v[118:121]
	v_mfma_f32_16x16x32_bf16 v[114:117], v[172:175], v[184:187], v[114:117]
	v_mfma_f32_16x16x32_bf16 v[102:105], v[164:167], v[196:199], v[102:105]
	v_mfma_f32_16x16x32_bf16 v[98:101], v[172:175], v[196:199], v[98:101]
	v_mfma_f32_16x16x32_bf16 v[86:89], v[164:167], v[214:217], v[86:89]
	v_mfma_f32_16x16x32_bf16 v[82:85], v[172:175], v[214:217], v[82:85]
	v_mfma_f32_16x16x32_bf16 v[70:73], v[164:167], v[222:225], v[70:73]
	v_mfma_f32_16x16x32_bf16 v[66:69], v[172:175], v[222:225], v[66:69]
	v_mfma_f32_16x16x32_bf16 v[118:121], v[168:171], v[188:191], v[118:121]
	v_mfma_f32_16x16x32_bf16 v[114:117], v[176:179], v[188:191], v[114:117]
	v_mfma_f32_16x16x32_bf16 v[102:105], v[168:171], v[210:213], v[102:105]
	v_mfma_f32_16x16x32_bf16 v[98:101], v[176:179], v[210:213], v[98:101]
	v_mfma_f32_16x16x32_bf16 v[86:89], v[168:171], v[218:221], v[86:89]
	v_mfma_f32_16x16x32_bf16 v[82:85], v[176:179], v[218:221], v[82:85]
	v_mfma_f32_16x16x32_bf16 v[70:73], v[168:171], v[226:229], v[70:73]
	v_mfma_f32_16x16x32_bf16 v[66:69], v[176:179], v[226:229], v[66:69]
	s_barrier
	s_add_i32 s26, s28, s17
	v_lshl_add_u64 v[144:145], s[30:31], 0, v[0:1]
	s_mov_b32 m0, s26
	ds_read_b128 v[184:187], v150 offset:16384
	ds_read_b128 v[188:191], v150 offset:17408
	ds_read_b128 v[196:199], v150 offset:18432
	ds_read_b128 v[210:213], v150 offset:19456
	ds_read_b128 v[214:217], v150 offset:20480
	ds_read_b128 v[218:221], v150 offset:21504
	ds_read_b128 v[222:225], v150 offset:22528
	ds_read_b128 v[226:229], v150 offset:23552
	global_load_lds_dwordx4 v[144:145], off
	s_add_i32 m0, s26, 0x2000
	s_add_u32 s60, s30, 0x40000
	v_lshl_add_u64 v[180:181], s[30:31], 0, v[130:131]
	s_addc_u32 s61, s31, 0
	s_add_i32 s25, s25, s17
	global_load_lds_dwordx4 v[180:181], off
	v_lshl_add_u64 v[192:193], s[60:61], 0, v[0:1]
	s_mov_b32 m0, s25
	v_lshl_add_u64 v[202:203], s[36:37], 0, v[132:133]
	global_load_lds_dwordx4 v[192:193], off
	v_lshl_add_u64 v[192:193], s[60:61], 0, v[130:131]
	s_add_i32 m0, s25, 0x2000
	s_nop 0
	global_load_lds_dwordx4 v[192:193], off
	v_lshl_add_u64 v[192:193], s[36:37], 0, v[134:135]
	s_mov_b32 m0, s47
	s_nop 0
	global_load_lds_dwordx4 v[192:193], off
	s_mov_b32 m0, s48
	s_nop 0
	global_load_lds_dwordx4 v[202:203], off
	s_waitcnt vmcnt(8)
	s_waitcnt lgkmcnt(0)
	s_barrier
	v_mfma_f32_16x16x32_bf16 v[62:65], v[140:143], v[184:187], v[62:65]
	v_mfma_f32_16x16x32_bf16 v[58:61], v[156:159], v[184:187], v[58:61]
	v_mfma_f32_16x16x32_bf16 v[46:49], v[140:143], v[196:199], v[46:49]
	v_mfma_f32_16x16x32_bf16 v[42:45], v[156:159], v[196:199], v[42:45]
	v_mfma_f32_16x16x32_bf16 v[30:33], v[140:143], v[214:217], v[30:33]
	v_mfma_f32_16x16x32_bf16 v[26:29], v[156:159], v[214:217], v[26:29]
	v_mfma_f32_16x16x32_bf16 v[14:17], v[140:143], v[222:225], v[14:17]
	v_mfma_f32_16x16x32_bf16 v[10:13], v[156:159], v[222:225], v[10:13]
	v_mfma_f32_16x16x32_bf16 v[62:65], v[152:155], v[188:191], v[62:65]
	v_mfma_f32_16x16x32_bf16 v[58:61], v[160:163], v[188:191], v[58:61]
	v_mfma_f32_16x16x32_bf16 v[46:49], v[152:155], v[210:213], v[46:49]
	v_mfma_f32_16x16x32_bf16 v[42:45], v[160:163], v[210:213], v[42:45]
	v_mfma_f32_16x16x32_bf16 v[30:33], v[152:155], v[218:221], v[30:33]
	v_mfma_f32_16x16x32_bf16 v[26:29], v[160:163], v[218:221], v[26:29]
	v_mfma_f32_16x16x32_bf16 v[14:17], v[152:155], v[226:229], v[14:17]
	v_mfma_f32_16x16x32_bf16 v[10:13], v[160:163], v[226:229], v[10:13]
	v_mfma_f32_16x16x32_bf16 v[54:57], v[164:167], v[184:187], v[54:57]
	v_mfma_f32_16x16x32_bf16 v[50:53], v[172:175], v[184:187], v[50:53]
	v_mfma_f32_16x16x32_bf16 v[38:41], v[164:167], v[196:199], v[38:41]
	v_mfma_f32_16x16x32_bf16 v[34:37], v[172:175], v[196:199], v[34:37]
	v_mfma_f32_16x16x32_bf16 v[22:25], v[164:167], v[214:217], v[22:25]
	v_mfma_f32_16x16x32_bf16 v[18:21], v[172:175], v[214:217], v[18:21]
	v_mfma_f32_16x16x32_bf16 v[6:9], v[164:167], v[222:225], v[6:9]
	v_mfma_f32_16x16x32_bf16 v[2:5], v[172:175], v[222:225], v[2:5]
	v_mfma_f32_16x16x32_bf16 v[54:57], v[168:171], v[188:191], v[54:57]
	v_mfma_f32_16x16x32_bf16 v[50:53], v[176:179], v[188:191], v[50:53]
	v_mfma_f32_16x16x32_bf16 v[38:41], v[168:171], v[210:213], v[38:41]
	v_mfma_f32_16x16x32_bf16 v[34:37], v[176:179], v[210:213], v[34:37]
	v_mfma_f32_16x16x32_bf16 v[22:25], v[168:171], v[218:221], v[22:25]
	v_mfma_f32_16x16x32_bf16 v[18:21], v[176:179], v[218:221], v[18:21]
	v_mfma_f32_16x16x32_bf16 v[6:9], v[168:171], v[226:229], v[6:9]
	v_mfma_f32_16x16x32_bf16 v[2:5], v[176:179], v[226:229], v[2:5]
	s_barrier
	s_add_i32 s25, 0, 0x18000
	v_add_u32_e32 v151, s25, v147
	s_add_i32 s26, 0, 0x1c000
	ds_read_b128 v[140:143], v151
	ds_read_b128 v[152:155], v151 offset:1024
	ds_read_b128 v[156:159], v151 offset:2048
	ds_read_b128 v[160:163], v151 offset:3072
	v_add_u32_e32 v151, s26, v147
	ds_read_b128 v[164:167], v151
	ds_read_b128 v[168:171], v151 offset:1024
	ds_read_b128 v[172:175], v151 offset:2048
	ds_read_b128 v[176:179], v151 offset:3072
	s_add_u32 s36, s36, 0x40000
	s_addc_u32 s37, s37, 0
	s_mov_b32 m0, s49
	v_lshl_add_u64 v[230:231], s[36:37], 0, v[134:135]
	ds_read_b128 v[184:187], v150 offset:32768
	ds_read_b128 v[188:191], v150 offset:33792
	ds_read_b128 v[196:199], v150 offset:34816
	ds_read_b128 v[210:213], v150 offset:35840
	ds_read_b128 v[214:217], v150 offset:36864
	ds_read_b128 v[218:221], v150 offset:37888
	ds_read_b128 v[222:225], v150 offset:38912
	ds_read_b128 v[226:229], v150 offset:39936
	global_load_lds_dwordx4 v[230:231], off
	v_lshl_add_u64 v[230:231], s[36:37], 0, v[132:133]
	s_mov_b32 m0, s50
	s_nop 0
	global_load_lds_dwordx4 v[230:231], off
	s_waitcnt vmcnt(8)
	s_waitcnt lgkmcnt(0)
	s_barrier
	v_mfma_f32_16x16x32_bf16 v[126:129], v[140:143], v[184:187], v[126:129]
	v_mfma_f32_16x16x32_bf16 v[122:125], v[156:159], v[184:187], v[122:125]
	v_mfma_f32_16x16x32_bf16 v[110:113], v[140:143], v[196:199], v[110:113]
	v_mfma_f32_16x16x32_bf16 v[106:109], v[156:159], v[196:199], v[106:109]
	v_mfma_f32_16x16x32_bf16 v[94:97], v[140:143], v[214:217], v[94:97]
	v_mfma_f32_16x16x32_bf16 v[90:93], v[156:159], v[214:217], v[90:93]
	v_mfma_f32_16x16x32_bf16 v[78:81], v[140:143], v[222:225], v[78:81]
	v_mfma_f32_16x16x32_bf16 v[74:77], v[156:159], v[222:225], v[74:77]
	v_mfma_f32_16x16x32_bf16 v[126:129], v[152:155], v[188:191], v[126:129]
	v_mfma_f32_16x16x32_bf16 v[122:125], v[160:163], v[188:191], v[122:125]
	v_mfma_f32_16x16x32_bf16 v[110:113], v[152:155], v[210:213], v[110:113]
	v_mfma_f32_16x16x32_bf16 v[106:109], v[160:163], v[210:213], v[106:109]
	v_mfma_f32_16x16x32_bf16 v[94:97], v[152:155], v[218:221], v[94:97]
	v_mfma_f32_16x16x32_bf16 v[90:93], v[160:163], v[218:221], v[90:93]
	v_mfma_f32_16x16x32_bf16 v[78:81], v[152:155], v[226:229], v[78:81]
	v_mfma_f32_16x16x32_bf16 v[74:77], v[160:163], v[226:229], v[74:77]
	v_mfma_f32_16x16x32_bf16 v[118:121], v[164:167], v[184:187], v[118:121]
	v_mfma_f32_16x16x32_bf16 v[114:117], v[172:175], v[184:187], v[114:117]
	v_mfma_f32_16x16x32_bf16 v[102:105], v[164:167], v[196:199], v[102:105]
	v_mfma_f32_16x16x32_bf16 v[98:101], v[172:175], v[196:199], v[98:101]
	v_mfma_f32_16x16x32_bf16 v[86:89], v[164:167], v[214:217], v[86:89]
	v_mfma_f32_16x16x32_bf16 v[82:85], v[172:175], v[214:217], v[82:85]
	v_mfma_f32_16x16x32_bf16 v[70:73], v[164:167], v[222:225], v[70:73]
	v_mfma_f32_16x16x32_bf16 v[66:69], v[172:175], v[222:225], v[66:69]
	v_mfma_f32_16x16x32_bf16 v[118:121], v[168:171], v[188:191], v[118:121]
	v_mfma_f32_16x16x32_bf16 v[114:117], v[176:179], v[188:191], v[114:117]
	v_mfma_f32_16x16x32_bf16 v[102:105], v[168:171], v[210:213], v[102:105]
	v_mfma_f32_16x16x32_bf16 v[98:101], v[176:179], v[210:213], v[98:101]
	v_mfma_f32_16x16x32_bf16 v[86:89], v[168:171], v[218:221], v[86:89]
	v_mfma_f32_16x16x32_bf16 v[82:85], v[176:179], v[218:221], v[82:85]
	v_mfma_f32_16x16x32_bf16 v[70:73], v[168:171], v[226:229], v[70:73]
	v_mfma_f32_16x16x32_bf16 v[66:69], v[176:179], v[226:229], v[66:69]
	s_barrier
	s_add_i32 s25, s25, s17
	v_lshl_add_u64 v[144:145], v[144:145], 0, s[22:23]
	s_mov_b32 m0, s25
	ds_read_b128 v[184:187], v150 offset:49152
	ds_read_b128 v[188:191], v150 offset:50176
	ds_read_b128 v[196:199], v150 offset:51200
	ds_read_b128 v[210:213], v150 offset:52224
	ds_read_b128 v[214:217], v150 offset:53248
	ds_read_b128 v[218:221], v150 offset:54272
	ds_read_b128 v[222:225], v150 offset:55296
	ds_read_b128 v[226:229], v150 offset:56320
	global_load_lds_dwordx4 v[144:145], off
	s_add_i32 m0, s25, 0x2000
	s_add_u32 s30, s30, 0x40080
	v_lshl_add_u64 v[144:145], v[180:181], 0, s[22:23]
	s_addc_u32 s31, s31, 0
	s_add_i32 s25, s26, s17
	global_load_lds_dwordx4 v[144:145], off
	v_lshl_add_u64 v[144:145], s[30:31], 0, v[0:1]
	s_mov_b32 m0, s25
	s_nop 0
	global_load_lds_dwordx4 v[144:145], off
	v_lshl_add_u64 v[144:145], s[30:31], 0, v[130:131]
	s_add_i32 m0, s25, 0x2000
	s_nop 0
	global_load_lds_dwordx4 v[144:145], off
	v_lshl_add_u64 v[144:145], v[192:193], 0, s[22:23]
	s_mov_b32 m0, s54
	s_nop 0
	global_load_lds_dwordx4 v[144:145], off
	v_lshl_add_u64 v[144:145], v[202:203], 0, s[22:23]
	s_mov_b32 m0, s55
	s_nop 0
	global_load_lds_dwordx4 v[144:145], off
	s_waitcnt vmcnt(8)
	s_waitcnt lgkmcnt(0)
	s_barrier
	v_mfma_f32_16x16x32_bf16 v[62:65], v[140:143], v[184:187], v[62:65]
	v_mfma_f32_16x16x32_bf16 v[58:61], v[156:159], v[184:187], v[58:61]
	v_mfma_f32_16x16x32_bf16 v[46:49], v[140:143], v[196:199], v[46:49]
	v_mfma_f32_16x16x32_bf16 v[42:45], v[156:159], v[196:199], v[42:45]
	v_mfma_f32_16x16x32_bf16 v[30:33], v[140:143], v[214:217], v[30:33]
	v_mfma_f32_16x16x32_bf16 v[26:29], v[156:159], v[214:217], v[26:29]
	v_mfma_f32_16x16x32_bf16 v[14:17], v[140:143], v[222:225], v[14:17]
	v_mfma_f32_16x16x32_bf16 v[10:13], v[156:159], v[222:225], v[10:13]
	v_mfma_f32_16x16x32_bf16 v[62:65], v[152:155], v[188:191], v[62:65]
	v_mfma_f32_16x16x32_bf16 v[58:61], v[160:163], v[188:191], v[58:61]
	v_mfma_f32_16x16x32_bf16 v[46:49], v[152:155], v[210:213], v[46:49]
	v_mfma_f32_16x16x32_bf16 v[42:45], v[160:163], v[210:213], v[42:45]
	v_mfma_f32_16x16x32_bf16 v[30:33], v[152:155], v[218:221], v[30:33]
	v_mfma_f32_16x16x32_bf16 v[26:29], v[160:163], v[218:221], v[26:29]
	v_mfma_f32_16x16x32_bf16 v[14:17], v[152:155], v[226:229], v[14:17]
	v_mfma_f32_16x16x32_bf16 v[10:13], v[160:163], v[226:229], v[10:13]
	v_mfma_f32_16x16x32_bf16 v[54:57], v[164:167], v[184:187], v[54:57]
	v_mfma_f32_16x16x32_bf16 v[50:53], v[172:175], v[184:187], v[50:53]
	v_mfma_f32_16x16x32_bf16 v[38:41], v[164:167], v[196:199], v[38:41]
	v_mfma_f32_16x16x32_bf16 v[34:37], v[172:175], v[196:199], v[34:37]
	v_mfma_f32_16x16x32_bf16 v[22:25], v[164:167], v[214:217], v[22:25]
	v_mfma_f32_16x16x32_bf16 v[18:21], v[172:175], v[214:217], v[18:21]
	v_mfma_f32_16x16x32_bf16 v[6:9], v[164:167], v[222:225], v[6:9]
	v_mfma_f32_16x16x32_bf16 v[2:5], v[172:175], v[222:225], v[2:5]
	v_mfma_f32_16x16x32_bf16 v[54:57], v[168:171], v[188:191], v[54:57]
	v_mfma_f32_16x16x32_bf16 v[50:53], v[176:179], v[188:191], v[50:53]
	v_mfma_f32_16x16x32_bf16 v[38:41], v[168:171], v[210:213], v[38:41]
	v_mfma_f32_16x16x32_bf16 v[34:37], v[176:179], v[210:213], v[34:37]
	v_mfma_f32_16x16x32_bf16 v[22:25], v[168:171], v[218:221], v[22:25]
	v_mfma_f32_16x16x32_bf16 v[18:21], v[176:179], v[218:221], v[18:21]
	v_mfma_f32_16x16x32_bf16 v[6:9], v[168:171], v[226:229], v[6:9]
	v_mfma_f32_16x16x32_bf16 v[2:5], v[176:179], v[226:229], v[2:5]
	s_barrier
	s_add_i32 s24, s24, 2
	s_add_u32 s12, s12, 0x100
	s_addc_u32 s13, s13, 0
	s_add_u32 s19, s19, 0x100
	s_addc_u32 s21, s21, 0
	s_cmp_gt_u32 s24, 13
	s_cbranch_scc0 .LBB0_986
	s_setprio 0
	s_and_b64 vcc, exec, s[10:11]
	s_cbranch_vccz .LBB0_989
	s_barrier
